# v76 + first K-loop trip peeled with C=0 MFMAs: the 128 accumulator-clearing v_mov per GEMM unit are gone
# speedup vs baseline: 1.0101x; 1.0076x over previous
.LBB0_266:
	s_xor_b64 s[2:3], s[2:3], -1
	s_mov_b32 s34, s74
	s_add_i32 s74, s74, 1
	s_cmp_lt_u32 s34, 5
	s_mov_b64 s[4:5], s[10:11]
	s_mov_b32 s10, s75
	s_cselect_b64 s[14:15], -1, 0
	s_add_i32 s75, s74, s16
	s_mov_b64 s[12:13], s[8:9]
	s_and_b64 s[8:9], s[14:15], exec
	s_cselect_b32 s8, s75, s10
	s_cselect_b32 s10, s6, s6
	s_ashr_i32 s11, s10, 31
	s_lshl_b64 s[10:11], s[10:11], 19
	s_add_u32 s10, s80, s10
	s_addc_u32 s11, s81, s11
	s_and_b64 s[44:45], s[14:15], exec
	s_cselect_b32 s44, s11, s5
	s_cselect_b32 s45, s10, s4
	s_ashr_i32 s9, s8, 31
	s_lshl_b64 s[8:9], s[8:9], 19
	v_readlane_b32 s47, v255, 14
	s_add_u32 s8, s47, s8
	v_readlane_b32 s47, v255, 15
	s_addc_u32 s9, s47, s9
	s_and_b64 s[14:15], s[14:15], exec
	s_cselect_b32 s47, s9, s13
	s_cselect_b32 s55, s8, s12
	s_add_u32 s4, s4, 0x40080
	s_addc_u32 s5, s5, 0
	s_add_u32 s78, s12, 0x100
	s_addc_u32 s79, s13, 0
	s_mov_b32 s85, -2
	s_waitcnt lgkmcnt(0)
	s_add_i32 s86, 0, 0x10000
	v_add_u32_e32 v0, s86, v150
	v_add_u32_e32 v189, 0x10000, v150
	ds_read_b128 v[142:145], v0
	ds_read_b128 v[146:149], v0 offset:1024
	ds_read_b128 v[152:155], v0 offset:2048
	ds_read_b128 v[156:159], v0 offset:3072
	s_add_u32 s12, s4, 0xfffc0080
	s_addc_u32 s13, s5, -1
	s_cmp_eq_u32 s85, 12
	s_cselect_b32 s15, s44, s13
	s_cselect_b32 s14, s45, s12
	s_cselect_b32 s13, s47, s79
	s_cselect_b32 s12, s55, s78
	s_add_i32 m0, s7, 0xc000
	ds_read_b128 v[160:163], v151
	ds_read_b128 v[164:167], v151 offset:1024
	ds_read_b128 v[168:171], v151 offset:2048
	ds_read_b128 v[172:175], v151 offset:3072
	ds_read_b128 v[176:179], v151 offset:4096
	ds_read_b128 v[180:183], v151 offset:5120
	ds_read_b128 v[184:187], v151 offset:6144
	ds_read_b128 v[190:193], v151 offset:7168
	global_load_lds_dwordx4 v138, s[4:5]
	s_add_i32 m0, s7, 0xe000
	s_nop 0
	global_load_lds_dwordx4 v140, s[4:5]
	s_waitcnt lgkmcnt(8)
	s_barrier
	s_waitcnt lgkmcnt(0)
	v_mfma_f32_16x16x32_bf16 v[126:129], v[142:145], v[160:163], 0
	v_mfma_f32_16x16x32_bf16 v[122:125], v[152:155], v[160:163], 0
	v_mfma_f32_16x16x32_bf16 v[110:113], v[142:145], v[168:171], 0
	v_mfma_f32_16x16x32_bf16 v[106:109], v[152:155], v[168:171], 0
	v_mfma_f32_16x16x32_bf16 v[94:97], v[142:145], v[176:179], 0
	v_mfma_f32_16x16x32_bf16 v[90:93], v[152:155], v[176:179], 0
	v_mfma_f32_16x16x32_bf16 v[78:81], v[142:145], v[184:187], 0
	v_mfma_f32_16x16x32_bf16 v[74:77], v[152:155], v[184:187], 0
	v_mfma_f32_16x16x32_bf16 v[126:129], v[146:149], v[164:167], v[126:129]
	v_mfma_f32_16x16x32_bf16 v[122:125], v[156:159], v[164:167], v[122:125]
	v_mfma_f32_16x16x32_bf16 v[110:113], v[146:149], v[172:175], v[110:113]
	v_mfma_f32_16x16x32_bf16 v[106:109], v[156:159], v[172:175], v[106:109]
	v_mfma_f32_16x16x32_bf16 v[94:97], v[146:149], v[180:183], v[94:97]
	v_mfma_f32_16x16x32_bf16 v[90:93], v[156:159], v[180:183], v[90:93]
	v_mfma_f32_16x16x32_bf16 v[78:81], v[146:149], v[190:193], v[78:81]
	v_mfma_f32_16x16x32_bf16 v[74:77], v[156:159], v[190:193], v[74:77]
	s_barrier
	s_add_i32 s88, 0, 0x14000
	s_add_i32 s86, s86, s22
	s_mov_b32 m0, s86
	ds_read_b128 v[194:197], v189 offset:16384
	ds_read_b128 v[198:201], v189 offset:17408
	ds_read_b128 v[202:205], v189 offset:18432
	ds_read_b128 v[206:209], v189 offset:19456
	global_load_lds_dwordx4 v134, s[12:13]
	s_add_i32 m0, s86, 0x2000
	s_nop 0
	global_load_lds_dwordx4 v130, s[12:13]
	s_barrier
	s_waitcnt lgkmcnt(0)
	v_mfma_f32_16x16x32_bf16 v[118:121], v[194:197], v[160:163], 0
	v_mfma_f32_16x16x32_bf16 v[114:117], v[202:205], v[160:163], 0
	v_mfma_f32_16x16x32_bf16 v[102:105], v[194:197], v[168:171], 0
	v_mfma_f32_16x16x32_bf16 v[98:101], v[202:205], v[168:171], 0
	v_mfma_f32_16x16x32_bf16 v[86:89], v[194:197], v[176:179], 0
	v_mfma_f32_16x16x32_bf16 v[82:85], v[202:205], v[176:179], 0
	v_mfma_f32_16x16x32_bf16 v[70:73], v[194:197], v[184:187], 0
	v_mfma_f32_16x16x32_bf16 v[66:69], v[202:205], v[184:187], 0
	v_mfma_f32_16x16x32_bf16 v[118:121], v[198:201], v[164:167], v[118:121]
	v_mfma_f32_16x16x32_bf16 v[114:117], v[206:209], v[164:167], v[114:117]
	v_mfma_f32_16x16x32_bf16 v[102:105], v[198:201], v[172:175], v[102:105]
	v_mfma_f32_16x16x32_bf16 v[98:101], v[206:209], v[172:175], v[98:101]
	v_mfma_f32_16x16x32_bf16 v[86:89], v[198:201], v[180:183], v[86:89]
	v_mfma_f32_16x16x32_bf16 v[82:85], v[206:209], v[180:183], v[82:85]
	v_mfma_f32_16x16x32_bf16 v[70:73], v[198:201], v[190:193], v[70:73]
	v_mfma_f32_16x16x32_bf16 v[66:69], v[206:209], v[190:193], v[66:69]
	s_mov_b32 m0, s7
	s_mov_b64 s[100:101], s[14:15]
	s_barrier
	ds_read_b128 v[160:163], v151 offset:16384
	ds_read_b128 v[164:167], v151 offset:17408
	ds_read_b128 v[168:171], v151 offset:18432
	ds_read_b128 v[172:175], v151 offset:19456
	ds_read_b128 v[176:179], v151 offset:20480
	ds_read_b128 v[180:183], v151 offset:21504
	ds_read_b128 v[184:187], v151 offset:22528
	ds_read_b128 v[190:193], v151 offset:23552
	global_load_lds_dwordx4 v136, s[100:101]
	s_mov_b32 m0, s23
	s_nop 0
	global_load_lds_dwordx4 v132, s[100:101]
	s_waitcnt vmcnt(10)
	s_barrier
	s_waitcnt lgkmcnt(0)
	v_mfma_f32_16x16x32_bf16 v[62:65], v[142:145], v[160:163], 0
	v_mfma_f32_16x16x32_bf16 v[58:61], v[152:155], v[160:163], 0
	v_mfma_f32_16x16x32_bf16 v[46:49], v[142:145], v[168:171], 0
	v_mfma_f32_16x16x32_bf16 v[42:45], v[152:155], v[168:171], 0
	v_mfma_f32_16x16x32_bf16 v[30:33], v[142:145], v[176:179], 0
	v_mfma_f32_16x16x32_bf16 v[26:29], v[152:155], v[176:179], 0
	v_mfma_f32_16x16x32_bf16 v[14:17], v[142:145], v[184:187], 0
	v_mfma_f32_16x16x32_bf16 v[10:13], v[152:155], v[184:187], 0
	v_mfma_f32_16x16x32_bf16 v[62:65], v[146:149], v[164:167], v[62:65]
	v_mfma_f32_16x16x32_bf16 v[58:61], v[156:159], v[164:167], v[58:61]
	v_mfma_f32_16x16x32_bf16 v[46:49], v[146:149], v[172:175], v[46:49]
	v_mfma_f32_16x16x32_bf16 v[42:45], v[156:159], v[172:175], v[42:45]
	v_mfma_f32_16x16x32_bf16 v[30:33], v[146:149], v[180:183], v[30:33]
	v_mfma_f32_16x16x32_bf16 v[26:29], v[156:159], v[180:183], v[26:29]
	v_mfma_f32_16x16x32_bf16 v[14:17], v[146:149], v[190:193], v[14:17]
	v_mfma_f32_16x16x32_bf16 v[10:13], v[156:159], v[190:193], v[10:13]
	s_barrier
	s_add_u32 s86, s12, 0x40000
	s_addc_u32 s87, s13, 0
	s_add_i32 s88, s88, s22
	s_mov_b32 m0, s88
	s_nop 0
	global_load_lds_dwordx4 v134, s[86:87]
	s_add_i32 m0, s88, 0x2000
	s_nop 0
	global_load_lds_dwordx4 v130, s[86:87]
	s_add_i32 s86, 0, 0x18000
	ds_read_b128 v[142:145], v189 offset:32768
	ds_read_b128 v[146:149], v189 offset:33792
	ds_read_b128 v[152:155], v189 offset:34816
	ds_read_b128 v[156:159], v189 offset:35840
	s_waitcnt vmcnt(6)
	s_barrier
	v_mfma_f32_16x16x32_bf16 v[54:57], v[194:197], v[160:163], 0
	v_mfma_f32_16x16x32_bf16 v[50:53], v[202:205], v[160:163], 0
	v_mfma_f32_16x16x32_bf16 v[38:41], v[194:197], v[168:171], 0
	v_mfma_f32_16x16x32_bf16 v[34:37], v[202:205], v[168:171], 0
	v_mfma_f32_16x16x32_bf16 v[22:25], v[194:197], v[176:179], 0
	v_mfma_f32_16x16x32_bf16 v[18:21], v[202:205], v[176:179], 0
	v_mfma_f32_16x16x32_bf16 v[6:9], v[194:197], v[184:187], 0
	v_mfma_f32_16x16x32_bf16 v[2:5], v[202:205], v[184:187], 0
	v_mfma_f32_16x16x32_bf16 v[54:57], v[198:201], v[164:167], v[54:57]
	v_mfma_f32_16x16x32_bf16 v[50:53], v[206:209], v[164:167], v[50:53]
	v_mfma_f32_16x16x32_bf16 v[38:41], v[198:201], v[172:175], v[38:41]
	v_mfma_f32_16x16x32_bf16 v[34:37], v[206:209], v[172:175], v[34:37]
	v_mfma_f32_16x16x32_bf16 v[22:25], v[198:201], v[180:183], v[22:25]
	v_mfma_f32_16x16x32_bf16 v[18:21], v[206:209], v[180:183], v[18:21]
	v_mfma_f32_16x16x32_bf16 v[6:9], v[198:201], v[190:193], v[6:9]
	v_mfma_f32_16x16x32_bf16 v[2:5], v[206:209], v[190:193], v[2:5]
	s_barrier
	s_add_u32 s14, s14, 0x40000
	s_addc_u32 s15, s15, 0
	s_mov_b32 m0, s28
	ds_read_b128 v[160:163], v151 offset:32768
	ds_read_b128 v[164:167], v151 offset:33792
	ds_read_b128 v[168:171], v151 offset:34816
	ds_read_b128 v[172:175], v151 offset:35840
	ds_read_b128 v[176:179], v151 offset:36864
	ds_read_b128 v[180:183], v151 offset:37888
	ds_read_b128 v[184:187], v151 offset:38912
	ds_read_b128 v[190:193], v151 offset:39936
	global_load_lds_dwordx4 v136, s[14:15]
	s_mov_b32 m0, s29
	s_nop 0
	global_load_lds_dwordx4 v132, s[14:15]
	s_waitcnt lgkmcnt(8)
	s_barrier
	s_waitcnt lgkmcnt(0)
	v_mfma_f32_16x16x32_bf16 v[126:129], v[142:145], v[160:163], v[126:129]
	v_mfma_f32_16x16x32_bf16 v[122:125], v[152:155], v[160:163], v[122:125]
	v_mfma_f32_16x16x32_bf16 v[110:113], v[142:145], v[168:171], v[110:113]
	v_mfma_f32_16x16x32_bf16 v[106:109], v[152:155], v[168:171], v[106:109]
	v_mfma_f32_16x16x32_bf16 v[94:97], v[142:145], v[176:179], v[94:97]
	v_mfma_f32_16x16x32_bf16 v[90:93], v[152:155], v[176:179], v[90:93]
	v_mfma_f32_16x16x32_bf16 v[78:81], v[142:145], v[184:187], v[78:81]
	v_mfma_f32_16x16x32_bf16 v[74:77], v[152:155], v[184:187], v[74:77]
	v_mfma_f32_16x16x32_bf16 v[126:129], v[146:149], v[164:167], v[126:129]
	v_mfma_f32_16x16x32_bf16 v[122:125], v[156:159], v[164:167], v[122:125]
	v_mfma_f32_16x16x32_bf16 v[110:113], v[146:149], v[172:175], v[110:113]
	v_mfma_f32_16x16x32_bf16 v[106:109], v[156:159], v[172:175], v[106:109]
	v_mfma_f32_16x16x32_bf16 v[94:97], v[146:149], v[180:183], v[94:97]
	v_mfma_f32_16x16x32_bf16 v[90:93], v[156:159], v[180:183], v[90:93]
	v_mfma_f32_16x16x32_bf16 v[78:81], v[146:149], v[190:193], v[78:81]
	v_mfma_f32_16x16x32_bf16 v[74:77], v[156:159], v[190:193], v[74:77]
	s_barrier
	s_add_i32 s14, 0, 0x1c000
	s_add_i32 s15, s86, s22
	s_mov_b32 m0, s15
	ds_read_b128 v[194:197], v189 offset:49152
	ds_read_b128 v[198:201], v189 offset:50176
	ds_read_b128 v[202:205], v189 offset:51200
	ds_read_b128 v[206:209], v189 offset:52224
	s_add_u32 s98, s12, s40
	s_addc_u32 s99, s13, s41
	global_load_lds_dwordx4 v134, s[98:99]
	s_add_i32 m0, s15, 0x2000
	s_add_u32 s98, s12, s40
	s_addc_u32 s99, s13, s41
	global_load_lds_dwordx4 v130, s[98:99]
	s_barrier
	s_waitcnt lgkmcnt(0)
	v_mfma_f32_16x16x32_bf16 v[118:121], v[194:197], v[160:163], v[118:121]
	v_mfma_f32_16x16x32_bf16 v[114:117], v[202:205], v[160:163], v[114:117]
	v_mfma_f32_16x16x32_bf16 v[102:105], v[194:197], v[168:171], v[102:105]
	v_mfma_f32_16x16x32_bf16 v[98:101], v[202:205], v[168:171], v[98:101]
	v_mfma_f32_16x16x32_bf16 v[86:89], v[194:197], v[176:179], v[86:89]
	v_mfma_f32_16x16x32_bf16 v[82:85], v[202:205], v[176:179], v[82:85]
	v_mfma_f32_16x16x32_bf16 v[70:73], v[194:197], v[184:187], v[70:73]
	v_mfma_f32_16x16x32_bf16 v[66:69], v[202:205], v[184:187], v[66:69]
	v_mfma_f32_16x16x32_bf16 v[118:121], v[198:201], v[164:167], v[118:121]
	v_mfma_f32_16x16x32_bf16 v[114:117], v[206:209], v[164:167], v[114:117]
	v_mfma_f32_16x16x32_bf16 v[102:105], v[198:201], v[172:175], v[102:105]
	v_mfma_f32_16x16x32_bf16 v[98:101], v[206:209], v[172:175], v[98:101]
	v_mfma_f32_16x16x32_bf16 v[86:89], v[198:201], v[180:183], v[86:89]
	v_mfma_f32_16x16x32_bf16 v[82:85], v[206:209], v[180:183], v[82:85]
	v_mfma_f32_16x16x32_bf16 v[70:73], v[198:201], v[190:193], v[70:73]
	v_mfma_f32_16x16x32_bf16 v[66:69], v[206:209], v[190:193], v[66:69]
	s_mov_b32 m0, s38
	s_barrier
	ds_read_b128 v[160:163], v151 offset:49152
	ds_read_b128 v[164:167], v151 offset:50176
	ds_read_b128 v[168:171], v151 offset:51200
	ds_read_b128 v[172:175], v151 offset:52224
	ds_read_b128 v[176:179], v151 offset:53248
	ds_read_b128 v[180:183], v151 offset:54272
	ds_read_b128 v[184:187], v151 offset:55296
	ds_read_b128 v[190:193], v151 offset:56320
	s_add_u32 s98, s100, s40
	s_addc_u32 s99, s101, s41
	global_load_lds_dwordx4 v136, s[98:99]
	s_mov_b32 m0, s39
	s_add_u32 s98, s100, s40
	s_addc_u32 s99, s101, s41
	global_load_lds_dwordx4 v132, s[98:99]
	s_waitcnt vmcnt(10)
	s_barrier
	s_waitcnt lgkmcnt(0)
	v_mfma_f32_16x16x32_bf16 v[62:65], v[142:145], v[160:163], v[62:65]
	v_mfma_f32_16x16x32_bf16 v[58:61], v[152:155], v[160:163], v[58:61]
	v_mfma_f32_16x16x32_bf16 v[46:49], v[142:145], v[168:171], v[46:49]
	v_mfma_f32_16x16x32_bf16 v[42:45], v[152:155], v[168:171], v[42:45]
	v_mfma_f32_16x16x32_bf16 v[30:33], v[142:145], v[176:179], v[30:33]
	v_mfma_f32_16x16x32_bf16 v[26:29], v[152:155], v[176:179], v[26:29]
	v_mfma_f32_16x16x32_bf16 v[14:17], v[142:145], v[184:187], v[14:17]
	v_mfma_f32_16x16x32_bf16 v[10:13], v[152:155], v[184:187], v[10:13]
	v_mfma_f32_16x16x32_bf16 v[62:65], v[146:149], v[164:167], v[62:65]
	v_mfma_f32_16x16x32_bf16 v[58:61], v[156:159], v[164:167], v[58:61]
	v_mfma_f32_16x16x32_bf16 v[46:49], v[146:149], v[172:175], v[46:49]
	v_mfma_f32_16x16x32_bf16 v[42:45], v[156:159], v[172:175], v[42:45]
	v_mfma_f32_16x16x32_bf16 v[30:33], v[146:149], v[180:183], v[30:33]
	v_mfma_f32_16x16x32_bf16 v[26:29], v[156:159], v[180:183], v[26:29]
	v_mfma_f32_16x16x32_bf16 v[14:17], v[146:149], v[190:193], v[14:17]
	v_mfma_f32_16x16x32_bf16 v[10:13], v[156:159], v[190:193], v[10:13]
	s_barrier
	s_add_u32 s12, s12, 0x40080
	s_addc_u32 s13, s13, 0
	s_add_i32 s14, s14, s22
	s_mov_b32 m0, s14
	s_nop 0
	global_load_lds_dwordx4 v134, s[12:13]
	s_add_i32 m0, s14, 0x2000
	s_nop 0
	global_load_lds_dwordx4 v130, s[12:13]
	s_add_i32 s86, 0, 0x10000
	ds_read_b128 v[142:145], v189
	ds_read_b128 v[146:149], v189 offset:1024
	ds_read_b128 v[152:155], v189 offset:2048
	ds_read_b128 v[156:159], v189 offset:3072
	s_waitcnt vmcnt(6)
	s_barrier
	v_mfma_f32_16x16x32_bf16 v[54:57], v[194:197], v[160:163], v[54:57]
	v_mfma_f32_16x16x32_bf16 v[50:53], v[202:205], v[160:163], v[50:53]
	v_mfma_f32_16x16x32_bf16 v[38:41], v[194:197], v[168:171], v[38:41]
	v_mfma_f32_16x16x32_bf16 v[34:37], v[202:205], v[168:171], v[34:37]
	v_mfma_f32_16x16x32_bf16 v[22:25], v[194:197], v[176:179], v[22:25]
	v_mfma_f32_16x16x32_bf16 v[18:21], v[202:205], v[176:179], v[18:21]
	v_mfma_f32_16x16x32_bf16 v[6:9], v[194:197], v[184:187], v[6:9]
	v_mfma_f32_16x16x32_bf16 v[2:5], v[202:205], v[184:187], v[2:5]
	v_mfma_f32_16x16x32_bf16 v[54:57], v[198:201], v[164:167], v[54:57]
	v_mfma_f32_16x16x32_bf16 v[50:53], v[206:209], v[164:167], v[50:53]
	v_mfma_f32_16x16x32_bf16 v[38:41], v[198:201], v[172:175], v[38:41]
	v_mfma_f32_16x16x32_bf16 v[34:37], v[206:209], v[172:175], v[34:37]
	v_mfma_f32_16x16x32_bf16 v[22:25], v[198:201], v[180:183], v[22:25]
	v_mfma_f32_16x16x32_bf16 v[18:21], v[206:209], v[180:183], v[18:21]
	v_mfma_f32_16x16x32_bf16 v[6:9], v[198:201], v[190:193], v[6:9]
	v_mfma_f32_16x16x32_bf16 v[2:5], v[206:209], v[190:193], v[2:5]
	s_add_i32 s85, s85, 2
	s_add_u32 s4, s4, 0x100
	s_addc_u32 s5, s5, 0
	s_add_u32 s78, s78, 0x100
	s_addc_u32 s79, s79, 0
	s_add_u32 s12, s4, 0xfffc0080
	s_addc_u32 s13, s5, -1
	s_cmp_eq_u32 s85, 12
	s_cselect_b32 s15, s44, s13
	s_cselect_b32 s14, s45, s12
	s_cselect_b32 s13, s47, s79
	s_cselect_b32 s12, s55, s78
	s_cmp_gt_u32 s85, 13
	s_barrier

.LBB0_837:
	s_ashr_i32 s15, s14, 31
	s_lshl_b64 s[78:79], s[14:15], 19
	s_add_u32 s84, s36, s78
	s_addc_u32 s85, s37, s79
	s_and_b64 s[4:5], s[4:5], exec
	s_cselect_b32 s15, s85, s91
	s_cselect_b32 s23, s84, s90
	s_add_u32 s34, s90, 0x100
	s_addc_u32 s75, s91, 0
	s_mov_b32 s78, -2
	s_waitcnt lgkmcnt(0)
	s_add_i32 s79, 0, 0x10000
	v_add_u32_e32 v142, s79, v212
	v_add_u32_e32 v189, 0x10000, v212
	ds_read_b128 v[130:133], v142
	ds_read_b128 v[134:137], v142 offset:1024
	ds_read_b128 v[138:141], v142 offset:2048
	ds_read_b128 v[142:145], v142 offset:3072
	s_add_u32 s4, s88, 0x100
	s_addc_u32 s5, s89, 0
	s_cmp_eq_u32 s78, 12
	s_cselect_b32 s93, s17, s5
	s_cselect_b32 s92, s16, s4
	s_cselect_b32 s91, s15, s75
	s_cselect_b32 s90, s23, s34
	v_lshl_add_u64 v[178:179], s[88:89], 0, v[196:197]
	s_add_i32 m0, s39, 0xc000
	ds_read_b128 v[146:149], v213
	ds_read_b128 v[150:153], v213 offset:1024
	ds_read_b128 v[154:157], v213 offset:2048
	ds_read_b128 v[158:161], v213 offset:3072
	ds_read_b128 v[162:165], v213 offset:4096
	ds_read_b128 v[166:169], v213 offset:5120
	ds_read_b128 v[170:173], v213 offset:6144
	ds_read_b128 v[174:177], v213 offset:7168
	global_load_lds_dwordx4 v[178:179], off
	s_add_i32 m0, s39, 0xe000
	v_lshl_add_u64 v[178:179], s[88:89], 0, v[198:199]
	global_load_lds_dwordx4 v[178:179], off
	s_waitcnt lgkmcnt(8)
	s_barrier
	s_waitcnt lgkmcnt(0)
	v_mfma_f32_16x16x32_bf16 v[126:129], v[130:133], v[146:149], 0
	v_mfma_f32_16x16x32_bf16 v[122:125], v[138:141], v[146:149], 0
	v_mfma_f32_16x16x32_bf16 v[110:113], v[130:133], v[154:157], 0
	v_mfma_f32_16x16x32_bf16 v[106:109], v[138:141], v[154:157], 0
	v_mfma_f32_16x16x32_bf16 v[94:97], v[130:133], v[162:165], 0
	v_mfma_f32_16x16x32_bf16 v[90:93], v[138:141], v[162:165], 0
	v_mfma_f32_16x16x32_bf16 v[78:81], v[130:133], v[170:173], 0
	v_mfma_f32_16x16x32_bf16 v[74:77], v[138:141], v[170:173], 0
	v_mfma_f32_16x16x32_bf16 v[126:129], v[134:137], v[150:153], v[126:129]
	v_mfma_f32_16x16x32_bf16 v[122:125], v[142:145], v[150:153], v[122:125]
	v_mfma_f32_16x16x32_bf16 v[110:113], v[134:137], v[158:161], v[110:113]
	v_mfma_f32_16x16x32_bf16 v[106:109], v[142:145], v[158:161], v[106:109]
	v_mfma_f32_16x16x32_bf16 v[94:97], v[134:137], v[166:169], v[94:97]
	v_mfma_f32_16x16x32_bf16 v[90:93], v[142:145], v[166:169], v[90:93]
	v_mfma_f32_16x16x32_bf16 v[78:81], v[134:137], v[174:177], v[78:81]
	v_mfma_f32_16x16x32_bf16 v[74:77], v[142:145], v[174:177], v[74:77]
	s_barrier
	s_add_i32 s87, 0, 0x14000
	s_add_i32 s79, s79, s38
	ds_read_b128 v[178:181], v189 offset:16384
	ds_read_b128 v[182:185], v189 offset:17408
	ds_read_b128 v[200:203], v189 offset:18432
	ds_read_b128 v[204:207], v189 offset:19456
	s_mov_b32 m0, s79
	global_load_lds_dwordx4 v0, s[90:91]
	s_add_i32 m0, s79, 0x2000
	s_nop 0
	global_load_lds_dwordx4 v194, s[90:91]
	s_barrier
	s_waitcnt lgkmcnt(0)
	v_mfma_f32_16x16x32_bf16 v[118:121], v[178:181], v[146:149], 0
	v_mfma_f32_16x16x32_bf16 v[114:117], v[200:203], v[146:149], 0
	v_mfma_f32_16x16x32_bf16 v[102:105], v[178:181], v[154:157], 0
	v_mfma_f32_16x16x32_bf16 v[98:101], v[200:203], v[154:157], 0
	v_mfma_f32_16x16x32_bf16 v[86:89], v[178:181], v[162:165], 0
	v_mfma_f32_16x16x32_bf16 v[82:85], v[200:203], v[162:165], 0
	v_mfma_f32_16x16x32_bf16 v[70:73], v[178:181], v[170:173], 0
	v_mfma_f32_16x16x32_bf16 v[66:69], v[200:203], v[170:173], 0
	v_mfma_f32_16x16x32_bf16 v[118:121], v[182:185], v[150:153], v[118:121]
	v_mfma_f32_16x16x32_bf16 v[114:117], v[204:207], v[150:153], v[114:117]
	v_mfma_f32_16x16x32_bf16 v[102:105], v[182:185], v[158:161], v[102:105]
	v_mfma_f32_16x16x32_bf16 v[98:101], v[204:207], v[158:161], v[98:101]
	v_mfma_f32_16x16x32_bf16 v[86:89], v[182:185], v[166:169], v[86:89]
	v_mfma_f32_16x16x32_bf16 v[82:85], v[204:207], v[166:169], v[82:85]
	v_mfma_f32_16x16x32_bf16 v[70:73], v[182:185], v[174:177], v[70:73]
	v_mfma_f32_16x16x32_bf16 v[66:69], v[204:207], v[174:177], v[66:69]
	s_mov_b32 m0, s39
	s_barrier
	ds_read_b128 v[146:149], v213 offset:16384
	ds_read_b128 v[150:153], v213 offset:17408
	ds_read_b128 v[154:157], v213 offset:18432
	ds_read_b128 v[158:161], v213 offset:19456
	ds_read_b128 v[162:165], v213 offset:20480
	ds_read_b128 v[166:169], v213 offset:21504
	ds_read_b128 v[170:173], v213 offset:22528
	ds_read_b128 v[174:177], v213 offset:23552
	global_load_lds_dwordx4 v190, s[92:93]
	s_mov_b32 m0, s42
	s_nop 0
	global_load_lds_dwordx4 v192, s[92:93]
	s_waitcnt vmcnt(10)
	s_barrier
	s_waitcnt lgkmcnt(0)
	v_mfma_f32_16x16x32_bf16 v[62:65], v[130:133], v[146:149], 0
	v_mfma_f32_16x16x32_bf16 v[58:61], v[138:141], v[146:149], 0
	v_mfma_f32_16x16x32_bf16 v[46:49], v[130:133], v[154:157], 0
	v_mfma_f32_16x16x32_bf16 v[42:45], v[138:141], v[154:157], 0
	v_mfma_f32_16x16x32_bf16 v[30:33], v[130:133], v[162:165], 0
	v_mfma_f32_16x16x32_bf16 v[26:29], v[138:141], v[162:165], 0
	v_mfma_f32_16x16x32_bf16 v[14:17], v[130:133], v[170:173], 0
	v_mfma_f32_16x16x32_bf16 v[10:13], v[138:141], v[170:173], 0
	v_mfma_f32_16x16x32_bf16 v[62:65], v[134:137], v[150:153], v[62:65]
	v_mfma_f32_16x16x32_bf16 v[58:61], v[142:145], v[150:153], v[58:61]
	v_mfma_f32_16x16x32_bf16 v[46:49], v[134:137], v[158:161], v[46:49]
	v_mfma_f32_16x16x32_bf16 v[42:45], v[142:145], v[158:161], v[42:45]
	v_mfma_f32_16x16x32_bf16 v[30:33], v[134:137], v[166:169], v[30:33]
	v_mfma_f32_16x16x32_bf16 v[26:29], v[142:145], v[166:169], v[26:29]
	v_mfma_f32_16x16x32_bf16 v[14:17], v[134:137], v[174:177], v[14:17]
	v_mfma_f32_16x16x32_bf16 v[10:13], v[142:145], v[174:177], v[10:13]
	s_barrier
	s_add_u32 s88, s90, 0x40000
	s_addc_u32 s89, s91, 0
	s_add_i32 s79, s87, s38
	s_mov_b32 m0, s79
	s_nop 0
	global_load_lds_dwordx4 v0, s[88:89]
	s_add_i32 m0, s79, 0x2000
	s_nop 0
	global_load_lds_dwordx4 v194, s[88:89]
	s_add_i32 s79, 0, 0x18000
	v_add_u32_e32 v142, s79, v212
	ds_read_b128 v[130:133], v142
	ds_read_b128 v[134:137], v142 offset:1024
	ds_read_b128 v[138:141], v142 offset:2048
	ds_read_b128 v[142:145], v142 offset:3072
	s_waitcnt vmcnt(6)
	s_barrier
	v_mfma_f32_16x16x32_bf16 v[54:57], v[178:181], v[146:149], 0
	v_mfma_f32_16x16x32_bf16 v[50:53], v[200:203], v[146:149], 0
	v_mfma_f32_16x16x32_bf16 v[38:41], v[178:181], v[154:157], 0
	v_mfma_f32_16x16x32_bf16 v[34:37], v[200:203], v[154:157], 0
	v_mfma_f32_16x16x32_bf16 v[22:25], v[178:181], v[162:165], 0
	v_mfma_f32_16x16x32_bf16 v[18:21], v[200:203], v[162:165], 0
	v_mfma_f32_16x16x32_bf16 v[6:9], v[178:181], v[170:173], 0
	v_mfma_f32_16x16x32_bf16 v[2:5], v[200:203], v[170:173], 0
	v_mfma_f32_16x16x32_bf16 v[54:57], v[182:185], v[150:153], v[54:57]
	v_mfma_f32_16x16x32_bf16 v[50:53], v[204:207], v[150:153], v[50:53]
	v_mfma_f32_16x16x32_bf16 v[38:41], v[182:185], v[158:161], v[38:41]
	v_mfma_f32_16x16x32_bf16 v[34:37], v[204:207], v[158:161], v[34:37]
	v_mfma_f32_16x16x32_bf16 v[22:25], v[182:185], v[166:169], v[22:25]
	v_mfma_f32_16x16x32_bf16 v[18:21], v[204:207], v[166:169], v[18:21]
	v_mfma_f32_16x16x32_bf16 v[6:9], v[182:185], v[174:177], v[6:9]
	v_mfma_f32_16x16x32_bf16 v[2:5], v[204:207], v[174:177], v[2:5]
	s_barrier
	s_add_u32 s88, s92, 0xc0000
	s_addc_u32 s89, s93, 0
	s_mov_b32 m0, s43
	ds_read_b128 v[146:149], v213 offset:32768
	ds_read_b128 v[150:153], v213 offset:33792
	ds_read_b128 v[154:157], v213 offset:34816
	ds_read_b128 v[158:161], v213 offset:35840
	ds_read_b128 v[162:165], v213 offset:36864
	ds_read_b128 v[166:169], v213 offset:37888
	ds_read_b128 v[170:173], v213 offset:38912
	ds_read_b128 v[174:177], v213 offset:39936
	global_load_lds_dwordx4 v190, s[88:89]
	s_mov_b32 m0, s44
	s_nop 0
	global_load_lds_dwordx4 v192, s[88:89]
	s_waitcnt lgkmcnt(8)
	s_barrier
	s_waitcnt lgkmcnt(0)
	v_mfma_f32_16x16x32_bf16 v[126:129], v[130:133], v[146:149], v[126:129]
	v_mfma_f32_16x16x32_bf16 v[122:125], v[138:141], v[146:149], v[122:125]
	v_mfma_f32_16x16x32_bf16 v[110:113], v[130:133], v[154:157], v[110:113]
	v_mfma_f32_16x16x32_bf16 v[106:109], v[138:141], v[154:157], v[106:109]
	v_mfma_f32_16x16x32_bf16 v[94:97], v[130:133], v[162:165], v[94:97]
	v_mfma_f32_16x16x32_bf16 v[90:93], v[138:141], v[162:165], v[90:93]
	v_mfma_f32_16x16x32_bf16 v[78:81], v[130:133], v[170:173], v[78:81]
	v_mfma_f32_16x16x32_bf16 v[74:77], v[138:141], v[170:173], v[74:77]
	v_mfma_f32_16x16x32_bf16 v[126:129], v[134:137], v[150:153], v[126:129]
	v_mfma_f32_16x16x32_bf16 v[122:125], v[142:145], v[150:153], v[122:125]
	v_mfma_f32_16x16x32_bf16 v[110:113], v[134:137], v[158:161], v[110:113]
	v_mfma_f32_16x16x32_bf16 v[106:109], v[142:145], v[158:161], v[106:109]
	v_mfma_f32_16x16x32_bf16 v[94:97], v[134:137], v[166:169], v[94:97]
	v_mfma_f32_16x16x32_bf16 v[90:93], v[142:145], v[166:169], v[90:93]
	v_mfma_f32_16x16x32_bf16 v[78:81], v[134:137], v[174:177], v[78:81]
	v_mfma_f32_16x16x32_bf16 v[74:77], v[142:145], v[174:177], v[74:77]
	s_barrier
	s_add_i32 s87, 0, 0x1c000
	s_add_i32 s79, s79, s38
	v_add_u32_e32 v204, s87, v212
	s_mov_b32 m0, s79
	ds_read_b128 v[178:181], v204
	ds_read_b128 v[182:185], v204 offset:1024
	ds_read_b128 v[200:203], v204 offset:2048
	ds_read_b128 v[204:207], v204 offset:3072
	s_add_u32 s98, s90, s40
	s_addc_u32 s99, s91, s41
	global_load_lds_dwordx4 v0, s[98:99]
	s_add_i32 m0, s79, 0x2000
	s_add_u32 s98, s90, s40
	s_addc_u32 s99, s91, s41
	global_load_lds_dwordx4 v194, s[98:99]
	s_barrier
	s_waitcnt lgkmcnt(0)
	v_mfma_f32_16x16x32_bf16 v[118:121], v[178:181], v[146:149], v[118:121]
	v_mfma_f32_16x16x32_bf16 v[114:117], v[200:203], v[146:149], v[114:117]
	v_mfma_f32_16x16x32_bf16 v[102:105], v[178:181], v[154:157], v[102:105]
	v_mfma_f32_16x16x32_bf16 v[98:101], v[200:203], v[154:157], v[98:101]
	v_mfma_f32_16x16x32_bf16 v[86:89], v[178:181], v[162:165], v[86:89]
	v_mfma_f32_16x16x32_bf16 v[82:85], v[200:203], v[162:165], v[82:85]
	v_mfma_f32_16x16x32_bf16 v[70:73], v[178:181], v[170:173], v[70:73]
	v_mfma_f32_16x16x32_bf16 v[66:69], v[200:203], v[170:173], v[66:69]
	v_mfma_f32_16x16x32_bf16 v[118:121], v[182:185], v[150:153], v[118:121]
	v_mfma_f32_16x16x32_bf16 v[114:117], v[204:207], v[150:153], v[114:117]
	v_mfma_f32_16x16x32_bf16 v[102:105], v[182:185], v[158:161], v[102:105]
	v_mfma_f32_16x16x32_bf16 v[98:101], v[204:207], v[158:161], v[98:101]
	v_mfma_f32_16x16x32_bf16 v[86:89], v[182:185], v[166:169], v[86:89]
	v_mfma_f32_16x16x32_bf16 v[82:85], v[204:207], v[166:169], v[82:85]
	v_mfma_f32_16x16x32_bf16 v[70:73], v[182:185], v[174:177], v[70:73]
	v_mfma_f32_16x16x32_bf16 v[66:69], v[204:207], v[174:177], v[66:69]
	s_mov_b32 m0, s60
	s_barrier
	ds_read_b128 v[146:149], v213 offset:49152
	ds_read_b128 v[150:153], v213 offset:50176
	ds_read_b128 v[154:157], v213 offset:51200
	ds_read_b128 v[158:161], v213 offset:52224
	ds_read_b128 v[162:165], v213 offset:53248
	ds_read_b128 v[166:169], v213 offset:54272
	ds_read_b128 v[170:173], v213 offset:55296
	ds_read_b128 v[174:177], v213 offset:56320
	s_add_u32 s98, s92, s40
	s_addc_u32 s99, s93, s41
	global_load_lds_dwordx4 v190, s[98:99]
	s_mov_b32 m0, s61
	s_add_u32 s98, s92, s40
	s_addc_u32 s99, s93, s41
	global_load_lds_dwordx4 v192, s[98:99]
	s_waitcnt vmcnt(10)
	s_barrier
	s_waitcnt lgkmcnt(0)
	v_mfma_f32_16x16x32_bf16 v[62:65], v[130:133], v[146:149], v[62:65]
	v_mfma_f32_16x16x32_bf16 v[58:61], v[138:141], v[146:149], v[58:61]
	v_mfma_f32_16x16x32_bf16 v[46:49], v[130:133], v[154:157], v[46:49]
	v_mfma_f32_16x16x32_bf16 v[42:45], v[138:141], v[154:157], v[42:45]
	v_mfma_f32_16x16x32_bf16 v[30:33], v[130:133], v[162:165], v[30:33]
	v_mfma_f32_16x16x32_bf16 v[26:29], v[138:141], v[162:165], v[26:29]
	v_mfma_f32_16x16x32_bf16 v[14:17], v[130:133], v[170:173], v[14:17]
	v_mfma_f32_16x16x32_bf16 v[10:13], v[138:141], v[170:173], v[10:13]
	v_mfma_f32_16x16x32_bf16 v[62:65], v[134:137], v[150:153], v[62:65]
	v_mfma_f32_16x16x32_bf16 v[58:61], v[142:145], v[150:153], v[58:61]
	v_mfma_f32_16x16x32_bf16 v[46:49], v[134:137], v[158:161], v[46:49]
	v_mfma_f32_16x16x32_bf16 v[42:45], v[142:145], v[158:161], v[42:45]
	v_mfma_f32_16x16x32_bf16 v[30:33], v[134:137], v[166:169], v[30:33]
	v_mfma_f32_16x16x32_bf16 v[26:29], v[142:145], v[166:169], v[26:29]
	v_mfma_f32_16x16x32_bf16 v[14:17], v[134:137], v[174:177], v[14:17]
	v_mfma_f32_16x16x32_bf16 v[10:13], v[142:145], v[174:177], v[10:13]
	s_barrier
	s_add_u32 s88, s90, 0x40080
	s_addc_u32 s89, s91, 0
	s_add_i32 s79, s87, s38
	s_mov_b32 m0, s79
	s_nop 0
	global_load_lds_dwordx4 v0, s[88:89]
	s_add_i32 m0, s79, 0x2000
	s_nop 0
	global_load_lds_dwordx4 v194, s[88:89]
	s_add_i32 s79, 0, 0x10000
	ds_read_b128 v[130:133], v189
	ds_read_b128 v[134:137], v189 offset:1024
	ds_read_b128 v[138:141], v189 offset:2048
	ds_read_b128 v[142:145], v189 offset:3072
	s_waitcnt vmcnt(6)
	s_barrier
	v_mfma_f32_16x16x32_bf16 v[54:57], v[178:181], v[146:149], v[54:57]
	v_mfma_f32_16x16x32_bf16 v[50:53], v[200:203], v[146:149], v[50:53]
	v_mfma_f32_16x16x32_bf16 v[38:41], v[178:181], v[154:157], v[38:41]
	v_mfma_f32_16x16x32_bf16 v[34:37], v[200:203], v[154:157], v[34:37]
	v_mfma_f32_16x16x32_bf16 v[22:25], v[178:181], v[162:165], v[22:25]
	v_mfma_f32_16x16x32_bf16 v[18:21], v[200:203], v[162:165], v[18:21]
	v_mfma_f32_16x16x32_bf16 v[6:9], v[178:181], v[170:173], v[6:9]
	v_mfma_f32_16x16x32_bf16 v[2:5], v[200:203], v[170:173], v[2:5]
	v_mfma_f32_16x16x32_bf16 v[54:57], v[182:185], v[150:153], v[54:57]
	v_mfma_f32_16x16x32_bf16 v[50:53], v[204:207], v[150:153], v[50:53]
	v_mfma_f32_16x16x32_bf16 v[38:41], v[182:185], v[158:161], v[38:41]
	v_mfma_f32_16x16x32_bf16 v[34:37], v[204:207], v[158:161], v[34:37]
	v_mfma_f32_16x16x32_bf16 v[22:25], v[182:185], v[166:169], v[22:25]
	v_mfma_f32_16x16x32_bf16 v[18:21], v[204:207], v[166:169], v[18:21]
	v_mfma_f32_16x16x32_bf16 v[6:9], v[182:185], v[174:177], v[6:9]
	v_mfma_f32_16x16x32_bf16 v[2:5], v[204:207], v[174:177], v[2:5]
	s_add_i32 s78, s78, 2
	s_add_u32 s34, s34, 0x100
	s_addc_u32 s75, s75, 0
	s_mov_b64 s[88:89], s[4:5]
	s_add_u32 s4, s88, 0x100
	s_addc_u32 s5, s89, 0
	s_cmp_eq_u32 s78, 12
	s_cselect_b32 s93, s17, s5
	s_cselect_b32 s92, s16, s4
	s_cselect_b32 s91, s15, s75
	s_cselect_b32 s90, s23, s34
	s_cmp_gt_u32 s78, 13
	s_barrier

.LBB0_918:
	s_ashr_i32 s17, s16, 31
	s_lshl_b64 s[22:23], s[16:17], 19
	v_mov_b64_e32 v[2:3], 0xb00
	s_add_u32 s84, s8, s22
	v_cmp_lt_i64_e32 vcc, s[28:29], v[2:3]
	s_addc_u32 s85, s9, s23
	s_and_b64 s[22:23], vcc, exec
	s_cselect_b32 s17, s85, s7
	s_cselect_b32 s22, s84, s6
	s_ashr_i32 s15, s14, 31
	s_lshl_b64 s[28:29], s[14:15], 19
	s_add_u32 s86, s37, s28
	s_addc_u32 s87, s38, s29
	s_and_b64 s[28:29], vcc, exec
	s_cselect_b32 s15, s87, s89
	s_cselect_b32 s23, s86, s88
	s_add_u32 s28, s88, 0x100
	s_addc_u32 s29, s89, 0
	s_mov_b32 s45, -2
	s_add_i32 vcc_lo, 0, 0x10000
	v_add_u32_e32 v0, vcc_lo, v254
	v_add_u32_e32 v189, 0x10000, v254
	ds_read_b128 v[130:133], v0
	ds_read_b128 v[134:137], v0 offset:1024
	ds_read_b128 v[138:141], v0 offset:2048
	ds_read_b128 v[142:145], v0 offset:3072
	s_add_u32 s88, s6, 0x100
	s_addc_u32 s89, s7, 0
	s_cmp_eq_u32 s45, 12
	s_cselect_b32 s93, s17, s89
	s_cselect_b32 s92, s22, s88
	s_cselect_b32 s91, s15, s29
	s_cselect_b32 s90, s23, s28
	s_add_i32 m0, s43, 0xc000
	ds_read_b128 v[146:149], v253
	ds_read_b128 v[150:153], v253 offset:1024
	ds_read_b128 v[168:171], v253 offset:2048
	ds_read_b128 v[172:175], v253 offset:3072
	ds_read_b128 v[176:179], v253 offset:4096
	ds_read_b128 v[180:183], v253 offset:5120
	ds_read_b128 v[184:187], v253 offset:6144
	ds_read_b128 v[190:193], v253 offset:7168
	global_load_lds_dwordx4 v164, s[6:7]
	s_add_i32 m0, s43, 0xe000
	v_lshl_add_u64 v[154:155], s[6:7], 0, v[166:167]
	global_load_lds_dwordx4 v[154:155], off
	s_waitcnt lgkmcnt(8)
	s_barrier
	s_waitcnt lgkmcnt(0)
	v_mfma_f32_16x16x32_bf16 v[126:129], v[130:133], v[146:149], 0
	v_mfma_f32_16x16x32_bf16 v[70:73], v[138:141], v[146:149], 0
	v_mfma_f32_16x16x32_bf16 v[122:125], v[130:133], v[168:171], 0
	v_mfma_f32_16x16x32_bf16 v[74:77], v[138:141], v[168:171], 0
	v_mfma_f32_16x16x32_bf16 v[114:117], v[130:133], v[176:179], 0
	v_mfma_f32_16x16x32_bf16 v[66:69], v[138:141], v[176:179], 0
	v_mfma_f32_16x16x32_bf16 v[110:113], v[130:133], v[184:187], 0
	v_mfma_f32_16x16x32_bf16 v[78:81], v[138:141], v[184:187], 0
	v_mfma_f32_16x16x32_bf16 v[126:129], v[134:137], v[150:153], v[126:129]
	v_mfma_f32_16x16x32_bf16 v[70:73], v[142:145], v[150:153], v[70:73]
	v_mfma_f32_16x16x32_bf16 v[122:125], v[134:137], v[172:175], v[122:125]
	v_mfma_f32_16x16x32_bf16 v[74:77], v[142:145], v[172:175], v[74:77]
	v_mfma_f32_16x16x32_bf16 v[114:117], v[134:137], v[180:183], v[114:117]
	v_mfma_f32_16x16x32_bf16 v[66:69], v[142:145], v[180:183], v[66:69]
	v_mfma_f32_16x16x32_bf16 v[110:113], v[134:137], v[190:193], v[110:113]
	v_mfma_f32_16x16x32_bf16 v[78:81], v[142:145], v[190:193], v[78:81]
	s_barrier
	s_add_i32 vcc_hi, 0, 0x14000
	s_add_i32 s6, vcc_lo, s39
	s_mov_b32 m0, s6
	ds_read_b128 v[194:197], v189 offset:16384
	ds_read_b128 v[198:201], v189 offset:17408
	ds_read_b128 v[202:205], v189 offset:18432
	ds_read_b128 v[206:209], v189 offset:19456
	global_load_lds_dwordx4 v160, s[90:91]
	s_add_i32 m0, s6, 0x2000
	s_nop 0
	global_load_lds_dwordx4 v156, s[90:91]
	s_barrier
	s_waitcnt lgkmcnt(0)
	v_mfma_f32_16x16x32_bf16 v[118:121], v[194:197], v[146:149], 0
	v_mfma_f32_16x16x32_bf16 v[94:97], v[202:205], v[146:149], 0
	v_mfma_f32_16x16x32_bf16 v[106:109], v[194:197], v[168:171], 0
	v_mfma_f32_16x16x32_bf16 v[90:93], v[202:205], v[168:171], 0
	v_mfma_f32_16x16x32_bf16 v[102:105], v[194:197], v[176:179], 0
	v_mfma_f32_16x16x32_bf16 v[82:85], v[202:205], v[176:179], 0
	v_mfma_f32_16x16x32_bf16 v[98:101], v[194:197], v[184:187], 0
	v_mfma_f32_16x16x32_bf16 v[86:89], v[202:205], v[184:187], 0
	v_mfma_f32_16x16x32_bf16 v[118:121], v[198:201], v[150:153], v[118:121]
	v_mfma_f32_16x16x32_bf16 v[94:97], v[206:209], v[150:153], v[94:97]
	v_mfma_f32_16x16x32_bf16 v[106:109], v[198:201], v[172:175], v[106:109]
	v_mfma_f32_16x16x32_bf16 v[90:93], v[206:209], v[172:175], v[90:93]
	v_mfma_f32_16x16x32_bf16 v[102:105], v[198:201], v[180:183], v[102:105]
	v_mfma_f32_16x16x32_bf16 v[82:85], v[206:209], v[180:183], v[82:85]
	v_mfma_f32_16x16x32_bf16 v[98:101], v[198:201], v[190:193], v[98:101]
	v_mfma_f32_16x16x32_bf16 v[86:89], v[206:209], v[190:193], v[86:89]
	s_mov_b32 m0, s43
	s_mov_b64 s[100:101], s[92:93]
	s_barrier
	ds_read_b128 v[146:149], v253 offset:16384
	ds_read_b128 v[150:153], v253 offset:17408
	ds_read_b128 v[168:171], v253 offset:18432
	ds_read_b128 v[172:175], v253 offset:19456
	ds_read_b128 v[176:179], v253 offset:20480
	ds_read_b128 v[180:183], v253 offset:21504
	ds_read_b128 v[184:187], v253 offset:22528
	ds_read_b128 v[190:193], v253 offset:23552
	global_load_lds_dwordx4 v162, s[100:101]
	s_mov_b32 m0, s60
	s_nop 0
	global_load_lds_dwordx4 v158, s[100:101]
	s_waitcnt vmcnt(10)
	s_barrier
	s_waitcnt lgkmcnt(0)
	v_mfma_f32_16x16x32_bf16 v[62:65], v[130:133], v[146:149], 0
	v_mfma_f32_16x16x32_bf16 v[10:13], v[138:141], v[146:149], 0
	v_mfma_f32_16x16x32_bf16 v[58:61], v[130:133], v[168:171], 0
	v_mfma_f32_16x16x32_bf16 v[14:17], v[138:141], v[168:171], 0
	v_mfma_f32_16x16x32_bf16 v[54:57], v[130:133], v[176:179], 0
	v_mfma_f32_16x16x32_bf16 v[6:9], v[138:141], v[176:179], 0
	v_mfma_f32_16x16x32_bf16 v[42:45], v[130:133], v[184:187], 0
	v_mfma_f32_16x16x32_bf16 v[2:5], v[138:141], v[184:187], 0
	v_mfma_f32_16x16x32_bf16 v[62:65], v[134:137], v[150:153], v[62:65]
	v_mfma_f32_16x16x32_bf16 v[10:13], v[142:145], v[150:153], v[10:13]
	v_mfma_f32_16x16x32_bf16 v[58:61], v[134:137], v[172:175], v[58:61]
	v_mfma_f32_16x16x32_bf16 v[14:17], v[142:145], v[172:175], v[14:17]
	v_mfma_f32_16x16x32_bf16 v[54:57], v[134:137], v[180:183], v[54:57]
	v_mfma_f32_16x16x32_bf16 v[6:9], v[142:145], v[180:183], v[6:9]
	v_mfma_f32_16x16x32_bf16 v[42:45], v[134:137], v[190:193], v[42:45]
	v_mfma_f32_16x16x32_bf16 v[2:5], v[142:145], v[190:193], v[2:5]
	s_barrier
	s_add_u32 s6, s90, 0x40000
	s_addc_u32 s7, s91, 0
	s_add_i32 vcc_lo, vcc_hi, s39
	s_mov_b32 m0, vcc_lo
	s_nop 0
	global_load_lds_dwordx4 v160, s[6:7]
	s_add_i32 m0, vcc_lo, 0x2000
	s_nop 0
	global_load_lds_dwordx4 v156, s[6:7]
	s_add_i32 vcc_lo, 0, 0x18000
	ds_read_b128 v[130:133], v189 offset:32768
	ds_read_b128 v[134:137], v189 offset:33792
	ds_read_b128 v[138:141], v189 offset:34816
	ds_read_b128 v[142:145], v189 offset:35840
	s_waitcnt vmcnt(6)
	s_barrier
	v_mfma_f32_16x16x32_bf16 v[50:53], v[194:197], v[146:149], 0
	v_mfma_f32_16x16x32_bf16 v[26:29], v[202:205], v[146:149], 0
	v_mfma_f32_16x16x32_bf16 v[46:49], v[194:197], v[168:171], 0
	v_mfma_f32_16x16x32_bf16 v[30:33], v[202:205], v[168:171], 0
	v_mfma_f32_16x16x32_bf16 v[38:41], v[194:197], v[176:179], 0
	v_mfma_f32_16x16x32_bf16 v[22:25], v[202:205], v[176:179], 0
	v_mfma_f32_16x16x32_bf16 v[34:37], v[194:197], v[184:187], 0
	v_mfma_f32_16x16x32_bf16 v[18:21], v[202:205], v[184:187], 0
	v_mfma_f32_16x16x32_bf16 v[50:53], v[198:201], v[150:153], v[50:53]
	v_mfma_f32_16x16x32_bf16 v[26:29], v[206:209], v[150:153], v[26:29]
	v_mfma_f32_16x16x32_bf16 v[46:49], v[198:201], v[172:175], v[46:49]
	v_mfma_f32_16x16x32_bf16 v[30:33], v[206:209], v[172:175], v[30:33]
	v_mfma_f32_16x16x32_bf16 v[38:41], v[198:201], v[180:183], v[38:41]
	v_mfma_f32_16x16x32_bf16 v[22:25], v[206:209], v[180:183], v[22:25]
	v_mfma_f32_16x16x32_bf16 v[34:37], v[198:201], v[190:193], v[34:37]
	v_mfma_f32_16x16x32_bf16 v[18:21], v[206:209], v[190:193], v[18:21]
	s_barrier
	s_add_u32 s6, s92, 0x40000
	s_addc_u32 s7, s93, 0
	s_mov_b32 m0, s61
	ds_read_b128 v[146:149], v253 offset:32768
	ds_read_b128 v[150:153], v253 offset:33792
	ds_read_b128 v[168:171], v253 offset:34816
	ds_read_b128 v[172:175], v253 offset:35840
	ds_read_b128 v[176:179], v253 offset:36864
	ds_read_b128 v[180:183], v253 offset:37888
	ds_read_b128 v[184:187], v253 offset:38912
	ds_read_b128 v[190:193], v253 offset:39936
	global_load_lds_dwordx4 v162, s[6:7]
	s_mov_b32 m0, s72
	s_nop 0
	global_load_lds_dwordx4 v158, s[6:7]
	s_waitcnt lgkmcnt(8)
	s_barrier
	s_waitcnt lgkmcnt(0)
	v_mfma_f32_16x16x32_bf16 v[126:129], v[130:133], v[146:149], v[126:129]
	v_mfma_f32_16x16x32_bf16 v[70:73], v[138:141], v[146:149], v[70:73]
	v_mfma_f32_16x16x32_bf16 v[122:125], v[130:133], v[168:171], v[122:125]
	v_mfma_f32_16x16x32_bf16 v[74:77], v[138:141], v[168:171], v[74:77]
	v_mfma_f32_16x16x32_bf16 v[114:117], v[130:133], v[176:179], v[114:117]
	v_mfma_f32_16x16x32_bf16 v[66:69], v[138:141], v[176:179], v[66:69]
	v_mfma_f32_16x16x32_bf16 v[110:113], v[130:133], v[184:187], v[110:113]
	v_mfma_f32_16x16x32_bf16 v[78:81], v[138:141], v[184:187], v[78:81]
	v_mfma_f32_16x16x32_bf16 v[126:129], v[134:137], v[150:153], v[126:129]
	v_mfma_f32_16x16x32_bf16 v[70:73], v[142:145], v[150:153], v[70:73]
	v_mfma_f32_16x16x32_bf16 v[122:125], v[134:137], v[172:175], v[122:125]
	v_mfma_f32_16x16x32_bf16 v[74:77], v[142:145], v[172:175], v[74:77]
	v_mfma_f32_16x16x32_bf16 v[114:117], v[134:137], v[180:183], v[114:117]
	v_mfma_f32_16x16x32_bf16 v[66:69], v[142:145], v[180:183], v[66:69]
	v_mfma_f32_16x16x32_bf16 v[110:113], v[134:137], v[190:193], v[110:113]
	v_mfma_f32_16x16x32_bf16 v[78:81], v[142:145], v[190:193], v[78:81]
	s_barrier
	s_add_i32 s92, 0, 0x1c000
	s_add_i32 s6, vcc_lo, s39
	s_mov_b32 m0, s6
	ds_read_b128 v[194:197], v189 offset:49152
	ds_read_b128 v[198:201], v189 offset:50176
	ds_read_b128 v[202:205], v189 offset:51200
	ds_read_b128 v[206:209], v189 offset:52224
	s_add_u32 s98, s90, s40
	s_addc_u32 s99, s91, s41
	global_load_lds_dwordx4 v160, s[98:99]
	s_add_i32 m0, s6, 0x2000
	s_add_u32 s98, s90, s40
	s_addc_u32 s99, s91, s41
	global_load_lds_dwordx4 v156, s[98:99]
	s_barrier
	s_waitcnt lgkmcnt(0)
	v_mfma_f32_16x16x32_bf16 v[118:121], v[194:197], v[146:149], v[118:121]
	v_mfma_f32_16x16x32_bf16 v[94:97], v[202:205], v[146:149], v[94:97]
	v_mfma_f32_16x16x32_bf16 v[106:109], v[194:197], v[168:171], v[106:109]
	v_mfma_f32_16x16x32_bf16 v[90:93], v[202:205], v[168:171], v[90:93]
	v_mfma_f32_16x16x32_bf16 v[102:105], v[194:197], v[176:179], v[102:105]
	v_mfma_f32_16x16x32_bf16 v[82:85], v[202:205], v[176:179], v[82:85]
	v_mfma_f32_16x16x32_bf16 v[98:101], v[194:197], v[184:187], v[98:101]
	v_mfma_f32_16x16x32_bf16 v[86:89], v[202:205], v[184:187], v[86:89]
	v_mfma_f32_16x16x32_bf16 v[118:121], v[198:201], v[150:153], v[118:121]
	v_mfma_f32_16x16x32_bf16 v[94:97], v[206:209], v[150:153], v[94:97]
	v_mfma_f32_16x16x32_bf16 v[106:109], v[198:201], v[172:175], v[106:109]
	v_mfma_f32_16x16x32_bf16 v[90:93], v[206:209], v[172:175], v[90:93]
	v_mfma_f32_16x16x32_bf16 v[102:105], v[198:201], v[180:183], v[102:105]
	v_mfma_f32_16x16x32_bf16 v[82:85], v[206:209], v[180:183], v[82:85]
	v_mfma_f32_16x16x32_bf16 v[98:101], v[198:201], v[190:193], v[98:101]
	v_mfma_f32_16x16x32_bf16 v[86:89], v[206:209], v[190:193], v[86:89]
	s_mov_b32 m0, s95
	s_barrier
	ds_read_b128 v[146:149], v253 offset:49152
	ds_read_b128 v[150:153], v253 offset:50176
	ds_read_b128 v[168:171], v253 offset:51200
	ds_read_b128 v[172:175], v253 offset:52224
	ds_read_b128 v[176:179], v253 offset:53248
	ds_read_b128 v[180:183], v253 offset:54272
	ds_read_b128 v[184:187], v253 offset:55296
	ds_read_b128 v[190:193], v253 offset:56320
	s_add_u32 s98, s100, s40
	s_addc_u32 s99, s101, s41
	global_load_lds_dwordx4 v162, s[98:99]
	s_mov_b32 m0, s96
	s_add_u32 s98, s100, s40
	s_addc_u32 s99, s101, s41
	global_load_lds_dwordx4 v158, s[98:99]
	s_waitcnt vmcnt(10)
	s_barrier
	s_waitcnt lgkmcnt(0)
	v_mfma_f32_16x16x32_bf16 v[62:65], v[130:133], v[146:149], v[62:65]
	v_mfma_f32_16x16x32_bf16 v[10:13], v[138:141], v[146:149], v[10:13]
	v_mfma_f32_16x16x32_bf16 v[58:61], v[130:133], v[168:171], v[58:61]
	v_mfma_f32_16x16x32_bf16 v[14:17], v[138:141], v[168:171], v[14:17]
	v_mfma_f32_16x16x32_bf16 v[54:57], v[130:133], v[176:179], v[54:57]
	v_mfma_f32_16x16x32_bf16 v[6:9], v[138:141], v[176:179], v[6:9]
	v_mfma_f32_16x16x32_bf16 v[42:45], v[130:133], v[184:187], v[42:45]
	v_mfma_f32_16x16x32_bf16 v[2:5], v[138:141], v[184:187], v[2:5]
	v_mfma_f32_16x16x32_bf16 v[62:65], v[134:137], v[150:153], v[62:65]
	v_mfma_f32_16x16x32_bf16 v[10:13], v[142:145], v[150:153], v[10:13]
	v_mfma_f32_16x16x32_bf16 v[58:61], v[134:137], v[172:175], v[58:61]
	v_mfma_f32_16x16x32_bf16 v[14:17], v[142:145], v[172:175], v[14:17]
	v_mfma_f32_16x16x32_bf16 v[54:57], v[134:137], v[180:183], v[54:57]
	v_mfma_f32_16x16x32_bf16 v[6:9], v[142:145], v[180:183], v[6:9]
	v_mfma_f32_16x16x32_bf16 v[42:45], v[134:137], v[190:193], v[42:45]
	v_mfma_f32_16x16x32_bf16 v[2:5], v[142:145], v[190:193], v[2:5]
	s_barrier
	s_add_u32 s6, s90, 0x40080
	s_addc_u32 s7, s91, 0
	s_add_i32 s90, s92, s39
	s_mov_b32 m0, s90
	s_nop 0
	global_load_lds_dwordx4 v160, s[6:7]
	s_add_i32 m0, s90, 0x2000
	s_nop 0
	global_load_lds_dwordx4 v156, s[6:7]
	s_add_i32 vcc_lo, 0, 0x10000
	ds_read_b128 v[130:133], v189
	ds_read_b128 v[134:137], v189 offset:1024
	ds_read_b128 v[138:141], v189 offset:2048
	ds_read_b128 v[142:145], v189 offset:3072
	s_waitcnt vmcnt(6)
	s_barrier
	v_mfma_f32_16x16x32_bf16 v[50:53], v[194:197], v[146:149], v[50:53]
	v_mfma_f32_16x16x32_bf16 v[26:29], v[202:205], v[146:149], v[26:29]
	v_mfma_f32_16x16x32_bf16 v[46:49], v[194:197], v[168:171], v[46:49]
	v_mfma_f32_16x16x32_bf16 v[30:33], v[202:205], v[168:171], v[30:33]
	v_mfma_f32_16x16x32_bf16 v[38:41], v[194:197], v[176:179], v[38:41]
	v_mfma_f32_16x16x32_bf16 v[22:25], v[202:205], v[176:179], v[22:25]
	v_mfma_f32_16x16x32_bf16 v[34:37], v[194:197], v[184:187], v[34:37]
	v_mfma_f32_16x16x32_bf16 v[18:21], v[202:205], v[184:187], v[18:21]
	v_mfma_f32_16x16x32_bf16 v[50:53], v[198:201], v[150:153], v[50:53]
	v_mfma_f32_16x16x32_bf16 v[26:29], v[206:209], v[150:153], v[26:29]
	v_mfma_f32_16x16x32_bf16 v[46:49], v[198:201], v[172:175], v[46:49]
	v_mfma_f32_16x16x32_bf16 v[30:33], v[206:209], v[172:175], v[30:33]
	v_mfma_f32_16x16x32_bf16 v[38:41], v[198:201], v[180:183], v[38:41]
	v_mfma_f32_16x16x32_bf16 v[22:25], v[206:209], v[180:183], v[22:25]
	v_mfma_f32_16x16x32_bf16 v[34:37], v[198:201], v[190:193], v[34:37]
	v_mfma_f32_16x16x32_bf16 v[18:21], v[206:209], v[190:193], v[18:21]
	s_add_i32 s45, s45, 2
	s_add_u32 s28, s28, 0x100
	s_addc_u32 s29, s29, 0
	s_mov_b64 s[6:7], s[88:89]
	s_add_u32 s88, s6, 0x100
	s_addc_u32 s89, s7, 0
	s_cmp_eq_u32 s45, 12
	s_cselect_b32 s93, s17, s89
	s_cselect_b32 s92, s22, s88
	s_cselect_b32 s91, s15, s29
	s_cselect_b32 s90, s23, s28
	s_cmp_gt_u32 s45, 13
	s_barrier

.LBB0_1089:
	s_add_u32 s34, s84, 0x100
	s_addc_u32 s78, s85, 0
	s_mov_b32 s79, -2
	s_waitcnt lgkmcnt(0)
	s_add_i32 s90, 0, 0x10000
	v_add_u32_e32 v142, s90, v212
	v_add_u32_e32 v189, 0x10000, v212
	ds_read_b128 v[130:133], v142
	ds_read_b128 v[134:137], v142 offset:1024
	ds_read_b128 v[138:141], v142 offset:2048
	ds_read_b128 v[142:145], v142 offset:3072
	s_add_u32 s84, s16, 0x100
	s_addc_u32 s85, s17, 0
	s_cmp_eq_u32 s79, 40
	s_cselect_b32 s89, s5, s85
	s_cselect_b32 s88, s4, s84
	s_cselect_b32 s87, s7, s78
	s_cselect_b32 s86, s6, s34
	v_lshl_add_u64 v[178:179], s[16:17], 0, v[196:197]
	s_add_i32 m0, s39, 0xc000
	ds_read_b128 v[146:149], v213
	ds_read_b128 v[150:153], v213 offset:1024
	ds_read_b128 v[154:157], v213 offset:2048
	ds_read_b128 v[158:161], v213 offset:3072
	ds_read_b128 v[162:165], v213 offset:4096
	ds_read_b128 v[166:169], v213 offset:5120
	ds_read_b128 v[170:173], v213 offset:6144
	ds_read_b128 v[174:177], v213 offset:7168
	global_load_lds_dwordx4 v[178:179], off
	s_add_i32 m0, s39, 0xe000
	v_lshl_add_u64 v[178:179], s[16:17], 0, v[198:199]
	global_load_lds_dwordx4 v[178:179], off
	s_waitcnt lgkmcnt(8)
	s_barrier
	s_waitcnt lgkmcnt(0)
	v_mfma_f32_16x16x32_bf16 v[126:129], v[130:133], v[146:149], 0
	v_mfma_f32_16x16x32_bf16 v[122:125], v[138:141], v[146:149], 0
	v_mfma_f32_16x16x32_bf16 v[110:113], v[130:133], v[154:157], 0
	v_mfma_f32_16x16x32_bf16 v[106:109], v[138:141], v[154:157], 0
	v_mfma_f32_16x16x32_bf16 v[94:97], v[130:133], v[162:165], 0
	v_mfma_f32_16x16x32_bf16 v[90:93], v[138:141], v[162:165], 0
	v_mfma_f32_16x16x32_bf16 v[78:81], v[130:133], v[170:173], 0
	v_mfma_f32_16x16x32_bf16 v[74:77], v[138:141], v[170:173], 0
	v_mfma_f32_16x16x32_bf16 v[126:129], v[134:137], v[150:153], v[126:129]
	v_mfma_f32_16x16x32_bf16 v[122:125], v[142:145], v[150:153], v[122:125]
	v_mfma_f32_16x16x32_bf16 v[110:113], v[134:137], v[158:161], v[110:113]
	v_mfma_f32_16x16x32_bf16 v[106:109], v[142:145], v[158:161], v[106:109]
	v_mfma_f32_16x16x32_bf16 v[94:97], v[134:137], v[166:169], v[94:97]
	v_mfma_f32_16x16x32_bf16 v[90:93], v[142:145], v[166:169], v[90:93]
	v_mfma_f32_16x16x32_bf16 v[78:81], v[134:137], v[174:177], v[78:81]
	v_mfma_f32_16x16x32_bf16 v[74:77], v[142:145], v[174:177], v[74:77]
	s_barrier
	s_add_i32 s91, 0, 0x14000
	s_add_i32 s16, s90, s38
	ds_read_b128 v[178:181], v189 offset:16384
	ds_read_b128 v[182:185], v189 offset:17408
	ds_read_b128 v[200:203], v189 offset:18432
	ds_read_b128 v[204:207], v189 offset:19456
	s_mov_b32 m0, s16
	global_load_lds_dwordx4 v0, s[86:87]
	s_add_i32 m0, s16, 0x2000
	s_nop 0
	global_load_lds_dwordx4 v194, s[86:87]
	s_barrier
	s_waitcnt lgkmcnt(0)
	v_mfma_f32_16x16x32_bf16 v[118:121], v[178:181], v[146:149], 0
	v_mfma_f32_16x16x32_bf16 v[114:117], v[200:203], v[146:149], 0
	v_mfma_f32_16x16x32_bf16 v[102:105], v[178:181], v[154:157], 0
	v_mfma_f32_16x16x32_bf16 v[98:101], v[200:203], v[154:157], 0
	v_mfma_f32_16x16x32_bf16 v[86:89], v[178:181], v[162:165], 0
	v_mfma_f32_16x16x32_bf16 v[82:85], v[200:203], v[162:165], 0
	v_mfma_f32_16x16x32_bf16 v[70:73], v[178:181], v[170:173], 0
	v_mfma_f32_16x16x32_bf16 v[66:69], v[200:203], v[170:173], 0
	v_mfma_f32_16x16x32_bf16 v[118:121], v[182:185], v[150:153], v[118:121]
	v_mfma_f32_16x16x32_bf16 v[114:117], v[204:207], v[150:153], v[114:117]
	v_mfma_f32_16x16x32_bf16 v[102:105], v[182:185], v[158:161], v[102:105]
	v_mfma_f32_16x16x32_bf16 v[98:101], v[204:207], v[158:161], v[98:101]
	v_mfma_f32_16x16x32_bf16 v[86:89], v[182:185], v[166:169], v[86:89]
	v_mfma_f32_16x16x32_bf16 v[82:85], v[204:207], v[166:169], v[82:85]
	v_mfma_f32_16x16x32_bf16 v[70:73], v[182:185], v[174:177], v[70:73]
	v_mfma_f32_16x16x32_bf16 v[66:69], v[204:207], v[174:177], v[66:69]
	s_mov_b32 m0, s39
	s_mov_b64 s[100:101], s[88:89]
	s_barrier
	ds_read_b128 v[146:149], v213 offset:16384
	ds_read_b128 v[150:153], v213 offset:17408
	ds_read_b128 v[154:157], v213 offset:18432
	ds_read_b128 v[158:161], v213 offset:19456
	ds_read_b128 v[162:165], v213 offset:20480
	ds_read_b128 v[166:169], v213 offset:21504
	ds_read_b128 v[170:173], v213 offset:22528
	ds_read_b128 v[174:177], v213 offset:23552
	global_load_lds_dwordx4 v190, s[100:101]
	s_mov_b32 m0, s42
	s_nop 0
	global_load_lds_dwordx4 v192, s[100:101]
	s_waitcnt vmcnt(10)
	s_barrier
	s_waitcnt lgkmcnt(0)
	v_mfma_f32_16x16x32_bf16 v[62:65], v[130:133], v[146:149], 0
	v_mfma_f32_16x16x32_bf16 v[58:61], v[138:141], v[146:149], 0
	v_mfma_f32_16x16x32_bf16 v[46:49], v[130:133], v[154:157], 0
	v_mfma_f32_16x16x32_bf16 v[42:45], v[138:141], v[154:157], 0
	v_mfma_f32_16x16x32_bf16 v[30:33], v[130:133], v[162:165], 0
	v_mfma_f32_16x16x32_bf16 v[26:29], v[138:141], v[162:165], 0
	v_mfma_f32_16x16x32_bf16 v[14:17], v[130:133], v[170:173], 0
	v_mfma_f32_16x16x32_bf16 v[10:13], v[138:141], v[170:173], 0
	v_mfma_f32_16x16x32_bf16 v[62:65], v[134:137], v[150:153], v[62:65]
	v_mfma_f32_16x16x32_bf16 v[58:61], v[142:145], v[150:153], v[58:61]
	v_mfma_f32_16x16x32_bf16 v[46:49], v[134:137], v[158:161], v[46:49]
	v_mfma_f32_16x16x32_bf16 v[42:45], v[142:145], v[158:161], v[42:45]
	v_mfma_f32_16x16x32_bf16 v[30:33], v[134:137], v[166:169], v[30:33]
	v_mfma_f32_16x16x32_bf16 v[26:29], v[142:145], v[166:169], v[26:29]
	v_mfma_f32_16x16x32_bf16 v[14:17], v[134:137], v[174:177], v[14:17]
	v_mfma_f32_16x16x32_bf16 v[10:13], v[142:145], v[174:177], v[10:13]
	s_barrier
	s_add_u32 s16, s86, 0xb0000
	s_addc_u32 s17, s87, 0
	s_add_i32 s90, s91, s38
	s_mov_b32 m0, s90
	s_nop 0
	global_load_lds_dwordx4 v0, s[16:17]
	s_add_i32 m0, s90, 0x2000
	s_nop 0
	global_load_lds_dwordx4 v194, s[16:17]
	s_add_i32 s90, 0, 0x18000
	v_add_u32_e32 v142, s90, v212
	ds_read_b128 v[130:133], v142
	ds_read_b128 v[134:137], v142 offset:1024
	ds_read_b128 v[138:141], v142 offset:2048
	ds_read_b128 v[142:145], v142 offset:3072
	s_waitcnt vmcnt(6)
	s_barrier
	v_mfma_f32_16x16x32_bf16 v[54:57], v[178:181], v[146:149], 0
	v_mfma_f32_16x16x32_bf16 v[50:53], v[200:203], v[146:149], 0
	v_mfma_f32_16x16x32_bf16 v[38:41], v[178:181], v[154:157], 0
	v_mfma_f32_16x16x32_bf16 v[34:37], v[200:203], v[154:157], 0
	v_mfma_f32_16x16x32_bf16 v[22:25], v[178:181], v[162:165], 0
	v_mfma_f32_16x16x32_bf16 v[18:21], v[200:203], v[162:165], 0
	v_mfma_f32_16x16x32_bf16 v[6:9], v[178:181], v[170:173], 0
	v_mfma_f32_16x16x32_bf16 v[2:5], v[200:203], v[170:173], 0
	v_mfma_f32_16x16x32_bf16 v[54:57], v[182:185], v[150:153], v[54:57]
	v_mfma_f32_16x16x32_bf16 v[50:53], v[204:207], v[150:153], v[50:53]
	v_mfma_f32_16x16x32_bf16 v[38:41], v[182:185], v[158:161], v[38:41]
	v_mfma_f32_16x16x32_bf16 v[34:37], v[204:207], v[158:161], v[34:37]
	v_mfma_f32_16x16x32_bf16 v[22:25], v[182:185], v[166:169], v[22:25]
	v_mfma_f32_16x16x32_bf16 v[18:21], v[204:207], v[166:169], v[18:21]
	v_mfma_f32_16x16x32_bf16 v[6:9], v[182:185], v[174:177], v[6:9]
	v_mfma_f32_16x16x32_bf16 v[2:5], v[204:207], v[174:177], v[2:5]
	s_barrier
	s_add_u32 s16, s88, 0xb0000
	s_addc_u32 s17, s89, 0
	s_mov_b32 m0, s43
	ds_read_b128 v[146:149], v213 offset:32768
	ds_read_b128 v[150:153], v213 offset:33792
	ds_read_b128 v[154:157], v213 offset:34816
	ds_read_b128 v[158:161], v213 offset:35840
	ds_read_b128 v[162:165], v213 offset:36864
	ds_read_b128 v[166:169], v213 offset:37888
	ds_read_b128 v[170:173], v213 offset:38912
	ds_read_b128 v[174:177], v213 offset:39936
	global_load_lds_dwordx4 v190, s[16:17]
	s_mov_b32 m0, s44
	s_nop 0
	global_load_lds_dwordx4 v192, s[16:17]
	s_waitcnt lgkmcnt(8)
	s_barrier
	s_waitcnt lgkmcnt(0)
	v_mfma_f32_16x16x32_bf16 v[126:129], v[130:133], v[146:149], v[126:129]
	v_mfma_f32_16x16x32_bf16 v[122:125], v[138:141], v[146:149], v[122:125]
	v_mfma_f32_16x16x32_bf16 v[110:113], v[130:133], v[154:157], v[110:113]
	v_mfma_f32_16x16x32_bf16 v[106:109], v[138:141], v[154:157], v[106:109]
	v_mfma_f32_16x16x32_bf16 v[94:97], v[130:133], v[162:165], v[94:97]
	v_mfma_f32_16x16x32_bf16 v[90:93], v[138:141], v[162:165], v[90:93]
	v_mfma_f32_16x16x32_bf16 v[78:81], v[130:133], v[170:173], v[78:81]
	v_mfma_f32_16x16x32_bf16 v[74:77], v[138:141], v[170:173], v[74:77]
	v_mfma_f32_16x16x32_bf16 v[126:129], v[134:137], v[150:153], v[126:129]
	v_mfma_f32_16x16x32_bf16 v[122:125], v[142:145], v[150:153], v[122:125]
	v_mfma_f32_16x16x32_bf16 v[110:113], v[134:137], v[158:161], v[110:113]
	v_mfma_f32_16x16x32_bf16 v[106:109], v[142:145], v[158:161], v[106:109]
	v_mfma_f32_16x16x32_bf16 v[94:97], v[134:137], v[166:169], v[94:97]
	v_mfma_f32_16x16x32_bf16 v[90:93], v[142:145], v[166:169], v[90:93]
	v_mfma_f32_16x16x32_bf16 v[78:81], v[134:137], v[174:177], v[78:81]
	v_mfma_f32_16x16x32_bf16 v[74:77], v[142:145], v[174:177], v[74:77]
	s_barrier
	s_add_i32 s88, 0, 0x1c000
	s_add_i32 s16, s90, s38
	v_add_u32_e32 v204, s88, v212
	s_mov_b32 m0, s16
	ds_read_b128 v[178:181], v204
	ds_read_b128 v[182:185], v204 offset:1024
	ds_read_b128 v[200:203], v204 offset:2048
	ds_read_b128 v[204:207], v204 offset:3072
	s_add_u32 s98, s86, s40
	s_addc_u32 s99, s87, s41
	global_load_lds_dwordx4 v0, s[98:99]
	s_add_i32 m0, s16, 0x2000
	s_add_u32 s98, s86, s40
	s_addc_u32 s99, s87, s41
	global_load_lds_dwordx4 v194, s[98:99]
	s_barrier
	s_waitcnt lgkmcnt(0)
	v_mfma_f32_16x16x32_bf16 v[118:121], v[178:181], v[146:149], v[118:121]
	v_mfma_f32_16x16x32_bf16 v[114:117], v[200:203], v[146:149], v[114:117]
	v_mfma_f32_16x16x32_bf16 v[102:105], v[178:181], v[154:157], v[102:105]
	v_mfma_f32_16x16x32_bf16 v[98:101], v[200:203], v[154:157], v[98:101]
	v_mfma_f32_16x16x32_bf16 v[86:89], v[178:181], v[162:165], v[86:89]
	v_mfma_f32_16x16x32_bf16 v[82:85], v[200:203], v[162:165], v[82:85]
	v_mfma_f32_16x16x32_bf16 v[70:73], v[178:181], v[170:173], v[70:73]
	v_mfma_f32_16x16x32_bf16 v[66:69], v[200:203], v[170:173], v[66:69]
	v_mfma_f32_16x16x32_bf16 v[118:121], v[182:185], v[150:153], v[118:121]
	v_mfma_f32_16x16x32_bf16 v[114:117], v[204:207], v[150:153], v[114:117]
	v_mfma_f32_16x16x32_bf16 v[102:105], v[182:185], v[158:161], v[102:105]
	v_mfma_f32_16x16x32_bf16 v[98:101], v[204:207], v[158:161], v[98:101]
	v_mfma_f32_16x16x32_bf16 v[86:89], v[182:185], v[166:169], v[86:89]
	v_mfma_f32_16x16x32_bf16 v[82:85], v[204:207], v[166:169], v[82:85]
	v_mfma_f32_16x16x32_bf16 v[70:73], v[182:185], v[174:177], v[70:73]
	v_mfma_f32_16x16x32_bf16 v[66:69], v[204:207], v[174:177], v[66:69]
	s_mov_b32 m0, s60
	s_barrier
	ds_read_b128 v[146:149], v213 offset:49152
	ds_read_b128 v[150:153], v213 offset:50176
	ds_read_b128 v[154:157], v213 offset:51200
	ds_read_b128 v[158:161], v213 offset:52224
	ds_read_b128 v[162:165], v213 offset:53248
	ds_read_b128 v[166:169], v213 offset:54272
	ds_read_b128 v[170:173], v213 offset:55296
	ds_read_b128 v[174:177], v213 offset:56320
	s_add_u32 s98, s100, s40
	s_addc_u32 s99, s101, s41
	global_load_lds_dwordx4 v190, s[98:99]
	s_mov_b32 m0, s61
	s_add_u32 s98, s100, s40
	s_addc_u32 s99, s101, s41
	global_load_lds_dwordx4 v192, s[98:99]
	s_waitcnt vmcnt(10)
	s_barrier
	s_waitcnt lgkmcnt(0)
	v_mfma_f32_16x16x32_bf16 v[62:65], v[130:133], v[146:149], v[62:65]
	v_mfma_f32_16x16x32_bf16 v[58:61], v[138:141], v[146:149], v[58:61]
	v_mfma_f32_16x16x32_bf16 v[46:49], v[130:133], v[154:157], v[46:49]
	v_mfma_f32_16x16x32_bf16 v[42:45], v[138:141], v[154:157], v[42:45]
	v_mfma_f32_16x16x32_bf16 v[30:33], v[130:133], v[162:165], v[30:33]
	v_mfma_f32_16x16x32_bf16 v[26:29], v[138:141], v[162:165], v[26:29]
	v_mfma_f32_16x16x32_bf16 v[14:17], v[130:133], v[170:173], v[14:17]
	v_mfma_f32_16x16x32_bf16 v[10:13], v[138:141], v[170:173], v[10:13]
	v_mfma_f32_16x16x32_bf16 v[62:65], v[134:137], v[150:153], v[62:65]
	v_mfma_f32_16x16x32_bf16 v[58:61], v[142:145], v[150:153], v[58:61]
	v_mfma_f32_16x16x32_bf16 v[46:49], v[134:137], v[158:161], v[46:49]
	v_mfma_f32_16x16x32_bf16 v[42:45], v[142:145], v[158:161], v[42:45]
	v_mfma_f32_16x16x32_bf16 v[30:33], v[134:137], v[166:169], v[30:33]
	v_mfma_f32_16x16x32_bf16 v[26:29], v[142:145], v[166:169], v[26:29]
	v_mfma_f32_16x16x32_bf16 v[14:17], v[134:137], v[174:177], v[14:17]
	v_mfma_f32_16x16x32_bf16 v[10:13], v[142:145], v[174:177], v[10:13]
	s_barrier
	s_add_u32 s16, s86, 0xb0080
	s_addc_u32 s17, s87, 0
	s_add_i32 s86, s88, s38
	s_mov_b32 m0, s86
	s_nop 0
	global_load_lds_dwordx4 v0, s[16:17]
	s_add_i32 m0, s86, 0x2000
	s_nop 0
	global_load_lds_dwordx4 v194, s[16:17]
	s_add_i32 s90, 0, 0x10000
	ds_read_b128 v[130:133], v189
	ds_read_b128 v[134:137], v189 offset:1024
	ds_read_b128 v[138:141], v189 offset:2048
	ds_read_b128 v[142:145], v189 offset:3072
	s_waitcnt vmcnt(6)
	s_barrier
	v_mfma_f32_16x16x32_bf16 v[54:57], v[178:181], v[146:149], v[54:57]
	v_mfma_f32_16x16x32_bf16 v[50:53], v[200:203], v[146:149], v[50:53]
	v_mfma_f32_16x16x32_bf16 v[38:41], v[178:181], v[154:157], v[38:41]
	v_mfma_f32_16x16x32_bf16 v[34:37], v[200:203], v[154:157], v[34:37]
	v_mfma_f32_16x16x32_bf16 v[22:25], v[178:181], v[162:165], v[22:25]
	v_mfma_f32_16x16x32_bf16 v[18:21], v[200:203], v[162:165], v[18:21]
	v_mfma_f32_16x16x32_bf16 v[6:9], v[178:181], v[170:173], v[6:9]
	v_mfma_f32_16x16x32_bf16 v[2:5], v[200:203], v[170:173], v[2:5]
	v_mfma_f32_16x16x32_bf16 v[54:57], v[182:185], v[150:153], v[54:57]
	v_mfma_f32_16x16x32_bf16 v[50:53], v[204:207], v[150:153], v[50:53]
	v_mfma_f32_16x16x32_bf16 v[38:41], v[182:185], v[158:161], v[38:41]
	v_mfma_f32_16x16x32_bf16 v[34:37], v[204:207], v[158:161], v[34:37]
	v_mfma_f32_16x16x32_bf16 v[22:25], v[182:185], v[166:169], v[22:25]
	v_mfma_f32_16x16x32_bf16 v[18:21], v[204:207], v[166:169], v[18:21]
	v_mfma_f32_16x16x32_bf16 v[6:9], v[182:185], v[174:177], v[6:9]
	v_mfma_f32_16x16x32_bf16 v[2:5], v[204:207], v[174:177], v[2:5]
	s_add_i32 s79, s79, 2
	s_add_u32 s34, s34, 0x100
	s_addc_u32 s78, s78, 0
	s_mov_b64 s[16:17], s[84:85]
	s_add_u32 s84, s16, 0x100
	s_addc_u32 s85, s17, 0
	s_cmp_eq_u32 s79, 40
	s_cselect_b32 s89, s5, s85
	s_cselect_b32 s88, s4, s84
	s_cselect_b32 s87, s7, s78
	s_cselect_b32 s86, s6, s34
	s_cmp_gt_u32 s79, 41
	s_barrier

.LBB0_1208:
	s_ashr_i32 s13, s12, 31
	v_cmp_lt_i64_e32 vcc, s[14:15], v[230:231]
	s_lshl_b64 s[14:15], s[12:13], 19
	s_add_u32 s14, s80, s14
	s_addc_u32 s15, s81, s15
	s_and_b64 s[16:17], vcc, exec
	s_cselect_b32 s13, s15, s89
	s_cselect_b32 s22, s14, s88
	s_ashr_i32 s7, s6, 31
	s_lshl_b64 s[16:17], s[6:7], 19
	s_add_u32 s16, s36, s16
	s_addc_u32 s17, s37, s17
	s_and_b64 s[92:93], vcc, exec
	s_cselect_b32 s7, s17, s91
	s_cselect_b32 s23, s16, s90
	s_add_u32 s88, s88, 0x40080
	s_addc_u32 s89, s89, 0
	s_add_u32 s34, s90, 0x100
	s_addc_u32 s79, s91, 0
	s_mov_b32 s85, -2
	s_waitcnt lgkmcnt(0)
	s_add_i32 s94, 0, 0x10000
	v_add_u32_e32 v0, s94, v170
	v_add_u32_e32 v189, 0x10000, v170
	ds_read_b128 v[130:133], v0
	ds_read_b128 v[134:137], v0 offset:1024
	ds_read_b128 v[138:141], v0 offset:2048
	ds_read_b128 v[142:145], v0 offset:3072
	s_add_u32 s87, s88, 0xfffc0080
	s_addc_u32 s90, s89, -1
	s_cmp_eq_u32 s85, 12
	s_cselect_b32 s93, s13, s90
	s_cselect_b32 s92, s22, s87
	s_cselect_b32 s91, s7, s79
	s_cselect_b32 s90, s23, s34
	s_waitcnt lgkmcnt(0)
	s_add_i32 m0, s39, 0xc000
	ds_read_b128 v[158:161], v171
	ds_read_b128 v[162:165], v171 offset:1024
	ds_read_b128 v[166:169], v171 offset:2048
	ds_read_b128 v[172:175], v171 offset:3072
	ds_read_b128 v[176:179], v171 offset:4096
	ds_read_b128 v[180:183], v171 offset:5120
	ds_read_b128 v[184:187], v171 offset:6144
	ds_read_b128 v[190:193], v171 offset:7168
	global_load_lds_dwordx4 v154, s[88:89]
	s_add_i32 m0, s39, 0xe000
	s_nop 0
	global_load_lds_dwordx4 v156, s[88:89]
	s_waitcnt lgkmcnt(8)
	s_barrier
	s_waitcnt lgkmcnt(0)
	v_mfma_f32_16x16x32_bf16 v[126:129], v[130:133], v[158:161], 0
	v_mfma_f32_16x16x32_bf16 v[122:125], v[138:141], v[158:161], 0
	v_mfma_f32_16x16x32_bf16 v[110:113], v[130:133], v[166:169], 0
	v_mfma_f32_16x16x32_bf16 v[106:109], v[138:141], v[166:169], 0
	v_mfma_f32_16x16x32_bf16 v[94:97], v[130:133], v[176:179], 0
	v_mfma_f32_16x16x32_bf16 v[90:93], v[138:141], v[176:179], 0
	v_mfma_f32_16x16x32_bf16 v[78:81], v[130:133], v[184:187], 0
	v_mfma_f32_16x16x32_bf16 v[74:77], v[138:141], v[184:187], 0
	v_mfma_f32_16x16x32_bf16 v[126:129], v[134:137], v[162:165], v[126:129]
	v_mfma_f32_16x16x32_bf16 v[122:125], v[142:145], v[162:165], v[122:125]
	v_mfma_f32_16x16x32_bf16 v[110:113], v[134:137], v[172:175], v[110:113]
	v_mfma_f32_16x16x32_bf16 v[106:109], v[142:145], v[172:175], v[106:109]
	v_mfma_f32_16x16x32_bf16 v[94:97], v[134:137], v[180:183], v[94:97]
	v_mfma_f32_16x16x32_bf16 v[90:93], v[142:145], v[180:183], v[90:93]
	v_mfma_f32_16x16x32_bf16 v[78:81], v[134:137], v[190:193], v[78:81]
	v_mfma_f32_16x16x32_bf16 v[74:77], v[142:145], v[190:193], v[74:77]
	s_barrier
	s_add_i32 s87, 0, 0x14000
	s_add_i32 s94, s94, s38
	s_mov_b32 m0, s94
	ds_read_b128 v[194:197], v189 offset:16384
	ds_read_b128 v[198:201], v189 offset:17408
	ds_read_b128 v[202:205], v189 offset:18432
	ds_read_b128 v[206:209], v189 offset:19456
	global_load_lds_dwordx4 v148, s[90:91]
	s_add_i32 m0, s94, 0x2000
	s_nop 0
	global_load_lds_dwordx4 v152, s[90:91]
	s_barrier
	s_waitcnt lgkmcnt(0)
	v_mfma_f32_16x16x32_bf16 v[118:121], v[194:197], v[158:161], 0
	v_mfma_f32_16x16x32_bf16 v[114:117], v[202:205], v[158:161], 0
	v_mfma_f32_16x16x32_bf16 v[102:105], v[194:197], v[166:169], 0
	v_mfma_f32_16x16x32_bf16 v[98:101], v[202:205], v[166:169], 0
	v_mfma_f32_16x16x32_bf16 v[86:89], v[194:197], v[176:179], 0
	v_mfma_f32_16x16x32_bf16 v[82:85], v[202:205], v[176:179], 0
	v_mfma_f32_16x16x32_bf16 v[70:73], v[194:197], v[184:187], 0
	v_mfma_f32_16x16x32_bf16 v[66:69], v[202:205], v[184:187], 0
	v_mfma_f32_16x16x32_bf16 v[118:121], v[198:201], v[162:165], v[118:121]
	v_mfma_f32_16x16x32_bf16 v[114:117], v[206:209], v[162:165], v[114:117]
	v_mfma_f32_16x16x32_bf16 v[102:105], v[198:201], v[172:175], v[102:105]
	v_mfma_f32_16x16x32_bf16 v[98:101], v[206:209], v[172:175], v[98:101]
	v_mfma_f32_16x16x32_bf16 v[86:89], v[198:201], v[180:183], v[86:89]
	v_mfma_f32_16x16x32_bf16 v[82:85], v[206:209], v[180:183], v[82:85]
	v_mfma_f32_16x16x32_bf16 v[70:73], v[198:201], v[190:193], v[70:73]
	v_mfma_f32_16x16x32_bf16 v[66:69], v[206:209], v[190:193], v[66:69]
	s_mov_b32 m0, s39
	s_mov_b64 s[100:101], s[92:93]
	s_barrier
	ds_read_b128 v[158:161], v171 offset:16384
	ds_read_b128 v[162:165], v171 offset:17408
	ds_read_b128 v[166:169], v171 offset:18432
	ds_read_b128 v[172:175], v171 offset:19456
	ds_read_b128 v[176:179], v171 offset:20480
	ds_read_b128 v[180:183], v171 offset:21504
	ds_read_b128 v[184:187], v171 offset:22528
	ds_read_b128 v[190:193], v171 offset:23552
	global_load_lds_dwordx4 v146, s[100:101]
	s_mov_b32 m0, s42
	s_nop 0
	global_load_lds_dwordx4 v150, s[100:101]
	s_waitcnt vmcnt(10)
	s_barrier
	s_waitcnt lgkmcnt(0)
	v_mfma_f32_16x16x32_bf16 v[62:65], v[130:133], v[158:161], 0
	v_mfma_f32_16x16x32_bf16 v[58:61], v[138:141], v[158:161], 0
	v_mfma_f32_16x16x32_bf16 v[46:49], v[130:133], v[166:169], 0
	v_mfma_f32_16x16x32_bf16 v[42:45], v[138:141], v[166:169], 0
	v_mfma_f32_16x16x32_bf16 v[30:33], v[130:133], v[176:179], 0
	v_mfma_f32_16x16x32_bf16 v[26:29], v[138:141], v[176:179], 0
	v_mfma_f32_16x16x32_bf16 v[14:17], v[130:133], v[184:187], 0
	v_mfma_f32_16x16x32_bf16 v[10:13], v[138:141], v[184:187], 0
	v_mfma_f32_16x16x32_bf16 v[62:65], v[134:137], v[162:165], v[62:65]
	v_mfma_f32_16x16x32_bf16 v[58:61], v[142:145], v[162:165], v[58:61]
	v_mfma_f32_16x16x32_bf16 v[46:49], v[134:137], v[172:175], v[46:49]
	v_mfma_f32_16x16x32_bf16 v[42:45], v[142:145], v[172:175], v[42:45]
	v_mfma_f32_16x16x32_bf16 v[30:33], v[134:137], v[180:183], v[30:33]
	v_mfma_f32_16x16x32_bf16 v[26:29], v[142:145], v[180:183], v[26:29]
	v_mfma_f32_16x16x32_bf16 v[14:17], v[134:137], v[190:193], v[14:17]
	v_mfma_f32_16x16x32_bf16 v[10:13], v[142:145], v[190:193], v[10:13]
	s_barrier
	s_add_u32 s94, s90, 0x40000
	s_addc_u32 s95, s91, 0
	s_add_i32 s87, s87, s38
	s_mov_b32 m0, s87
	s_nop 0
	global_load_lds_dwordx4 v148, s[94:95]
	s_add_i32 m0, s87, 0x2000
	s_nop 0
	global_load_lds_dwordx4 v152, s[94:95]
	s_add_i32 s87, 0, 0x18000
	ds_read_b128 v[130:133], v189 offset:32768
	ds_read_b128 v[134:137], v189 offset:33792
	ds_read_b128 v[138:141], v189 offset:34816
	ds_read_b128 v[142:145], v189 offset:35840
	s_waitcnt vmcnt(6)
	s_barrier
	v_mfma_f32_16x16x32_bf16 v[54:57], v[194:197], v[158:161], 0
	v_mfma_f32_16x16x32_bf16 v[50:53], v[202:205], v[158:161], 0
	v_mfma_f32_16x16x32_bf16 v[38:41], v[194:197], v[166:169], 0
	v_mfma_f32_16x16x32_bf16 v[34:37], v[202:205], v[166:169], 0
	v_mfma_f32_16x16x32_bf16 v[22:25], v[194:197], v[176:179], 0
	v_mfma_f32_16x16x32_bf16 v[18:21], v[202:205], v[176:179], 0
	v_mfma_f32_16x16x32_bf16 v[6:9], v[194:197], v[184:187], 0
	v_mfma_f32_16x16x32_bf16 v[2:5], v[202:205], v[184:187], 0
	v_mfma_f32_16x16x32_bf16 v[54:57], v[198:201], v[162:165], v[54:57]
	v_mfma_f32_16x16x32_bf16 v[50:53], v[206:209], v[162:165], v[50:53]
	v_mfma_f32_16x16x32_bf16 v[38:41], v[198:201], v[172:175], v[38:41]
	v_mfma_f32_16x16x32_bf16 v[34:37], v[206:209], v[172:175], v[34:37]
	v_mfma_f32_16x16x32_bf16 v[22:25], v[198:201], v[180:183], v[22:25]
	v_mfma_f32_16x16x32_bf16 v[18:21], v[206:209], v[180:183], v[18:21]
	v_mfma_f32_16x16x32_bf16 v[6:9], v[198:201], v[190:193], v[6:9]
	v_mfma_f32_16x16x32_bf16 v[2:5], v[206:209], v[190:193], v[2:5]
	s_barrier
	s_add_u32 s92, s92, 0x40000
	s_addc_u32 s93, s93, 0
	s_mov_b32 m0, s43
	ds_read_b128 v[158:161], v171 offset:32768
	ds_read_b128 v[162:165], v171 offset:33792
	ds_read_b128 v[166:169], v171 offset:34816
	ds_read_b128 v[172:175], v171 offset:35840
	ds_read_b128 v[176:179], v171 offset:36864
	ds_read_b128 v[180:183], v171 offset:37888
	ds_read_b128 v[184:187], v171 offset:38912
	ds_read_b128 v[190:193], v171 offset:39936
	global_load_lds_dwordx4 v146, s[92:93]
	s_mov_b32 m0, s44
	s_nop 0
	global_load_lds_dwordx4 v150, s[92:93]
	s_waitcnt lgkmcnt(8)
	s_barrier
	s_waitcnt lgkmcnt(0)
	v_mfma_f32_16x16x32_bf16 v[126:129], v[130:133], v[158:161], v[126:129]
	v_mfma_f32_16x16x32_bf16 v[122:125], v[138:141], v[158:161], v[122:125]
	v_mfma_f32_16x16x32_bf16 v[110:113], v[130:133], v[166:169], v[110:113]
	v_mfma_f32_16x16x32_bf16 v[106:109], v[138:141], v[166:169], v[106:109]
	v_mfma_f32_16x16x32_bf16 v[94:97], v[130:133], v[176:179], v[94:97]
	v_mfma_f32_16x16x32_bf16 v[90:93], v[138:141], v[176:179], v[90:93]
	v_mfma_f32_16x16x32_bf16 v[78:81], v[130:133], v[184:187], v[78:81]
	v_mfma_f32_16x16x32_bf16 v[74:77], v[138:141], v[184:187], v[74:77]
	v_mfma_f32_16x16x32_bf16 v[126:129], v[134:137], v[162:165], v[126:129]
	v_mfma_f32_16x16x32_bf16 v[122:125], v[142:145], v[162:165], v[122:125]
	v_mfma_f32_16x16x32_bf16 v[110:113], v[134:137], v[172:175], v[110:113]
	v_mfma_f32_16x16x32_bf16 v[106:109], v[142:145], v[172:175], v[106:109]
	v_mfma_f32_16x16x32_bf16 v[94:97], v[134:137], v[180:183], v[94:97]
	v_mfma_f32_16x16x32_bf16 v[90:93], v[142:145], v[180:183], v[90:93]
	v_mfma_f32_16x16x32_bf16 v[78:81], v[134:137], v[190:193], v[78:81]
	v_mfma_f32_16x16x32_bf16 v[74:77], v[142:145], v[190:193], v[74:77]
	s_barrier
	s_add_i32 s92, 0, 0x1c000
	s_add_i32 s87, s87, s38
	s_mov_b32 m0, s87
	ds_read_b128 v[194:197], v189 offset:49152
	ds_read_b128 v[198:201], v189 offset:50176
	ds_read_b128 v[202:205], v189 offset:51200
	ds_read_b128 v[206:209], v189 offset:52224
	s_add_u32 s98, s90, s40
	s_addc_u32 s99, s91, s41
	global_load_lds_dwordx4 v148, s[98:99]
	s_add_i32 m0, s87, 0x2000
	s_add_u32 s98, s90, s40
	s_addc_u32 s99, s91, s41
	global_load_lds_dwordx4 v152, s[98:99]
	s_barrier
	s_waitcnt lgkmcnt(0)
	v_mfma_f32_16x16x32_bf16 v[118:121], v[194:197], v[158:161], v[118:121]
	v_mfma_f32_16x16x32_bf16 v[114:117], v[202:205], v[158:161], v[114:117]
	v_mfma_f32_16x16x32_bf16 v[102:105], v[194:197], v[166:169], v[102:105]
	v_mfma_f32_16x16x32_bf16 v[98:101], v[202:205], v[166:169], v[98:101]
	v_mfma_f32_16x16x32_bf16 v[86:89], v[194:197], v[176:179], v[86:89]
	v_mfma_f32_16x16x32_bf16 v[82:85], v[202:205], v[176:179], v[82:85]
	v_mfma_f32_16x16x32_bf16 v[70:73], v[194:197], v[184:187], v[70:73]
	v_mfma_f32_16x16x32_bf16 v[66:69], v[202:205], v[184:187], v[66:69]
	v_mfma_f32_16x16x32_bf16 v[118:121], v[198:201], v[162:165], v[118:121]
	v_mfma_f32_16x16x32_bf16 v[114:117], v[206:209], v[162:165], v[114:117]
	v_mfma_f32_16x16x32_bf16 v[102:105], v[198:201], v[172:175], v[102:105]
	v_mfma_f32_16x16x32_bf16 v[98:101], v[206:209], v[172:175], v[98:101]
	v_mfma_f32_16x16x32_bf16 v[86:89], v[198:201], v[180:183], v[86:89]
	v_mfma_f32_16x16x32_bf16 v[82:85], v[206:209], v[180:183], v[82:85]
	v_mfma_f32_16x16x32_bf16 v[70:73], v[198:201], v[190:193], v[70:73]
	v_mfma_f32_16x16x32_bf16 v[66:69], v[206:209], v[190:193], v[66:69]
	s_mov_b32 m0, s60
	s_barrier
	ds_read_b128 v[158:161], v171 offset:49152
	ds_read_b128 v[162:165], v171 offset:50176
	ds_read_b128 v[166:169], v171 offset:51200
	ds_read_b128 v[172:175], v171 offset:52224
	ds_read_b128 v[176:179], v171 offset:53248
	ds_read_b128 v[180:183], v171 offset:54272
	ds_read_b128 v[184:187], v171 offset:55296
	ds_read_b128 v[190:193], v171 offset:56320
	s_add_u32 s98, s100, s40
	s_addc_u32 s99, s101, s41
	global_load_lds_dwordx4 v146, s[98:99]
	s_mov_b32 m0, s61
	s_add_u32 s98, s100, s40
	s_addc_u32 s99, s101, s41
	global_load_lds_dwordx4 v150, s[98:99]
	s_waitcnt vmcnt(10)
	s_barrier
	s_waitcnt lgkmcnt(0)
	v_mfma_f32_16x16x32_bf16 v[62:65], v[130:133], v[158:161], v[62:65]
	v_mfma_f32_16x16x32_bf16 v[58:61], v[138:141], v[158:161], v[58:61]
	v_mfma_f32_16x16x32_bf16 v[46:49], v[130:133], v[166:169], v[46:49]
	v_mfma_f32_16x16x32_bf16 v[42:45], v[138:141], v[166:169], v[42:45]
	v_mfma_f32_16x16x32_bf16 v[30:33], v[130:133], v[176:179], v[30:33]
	v_mfma_f32_16x16x32_bf16 v[26:29], v[138:141], v[176:179], v[26:29]
	v_mfma_f32_16x16x32_bf16 v[14:17], v[130:133], v[184:187], v[14:17]
	v_mfma_f32_16x16x32_bf16 v[10:13], v[138:141], v[184:187], v[10:13]
	v_mfma_f32_16x16x32_bf16 v[62:65], v[134:137], v[162:165], v[62:65]
	v_mfma_f32_16x16x32_bf16 v[58:61], v[142:145], v[162:165], v[58:61]
	v_mfma_f32_16x16x32_bf16 v[46:49], v[134:137], v[172:175], v[46:49]
	v_mfma_f32_16x16x32_bf16 v[42:45], v[142:145], v[172:175], v[42:45]
	v_mfma_f32_16x16x32_bf16 v[30:33], v[134:137], v[180:183], v[30:33]
	v_mfma_f32_16x16x32_bf16 v[26:29], v[142:145], v[180:183], v[26:29]
	v_mfma_f32_16x16x32_bf16 v[14:17], v[134:137], v[190:193], v[14:17]
	v_mfma_f32_16x16x32_bf16 v[10:13], v[142:145], v[190:193], v[10:13]
	s_barrier
	s_add_u32 s90, s90, 0x40080
	s_addc_u32 s91, s91, 0
	s_add_i32 s87, s92, s38
	s_mov_b32 m0, s87
	s_nop 0
	global_load_lds_dwordx4 v148, s[90:91]
	s_add_i32 m0, s87, 0x2000
	s_nop 0
	global_load_lds_dwordx4 v152, s[90:91]
	s_add_i32 s94, 0, 0x10000
	ds_read_b128 v[130:133], v189
	ds_read_b128 v[134:137], v189 offset:1024
	ds_read_b128 v[138:141], v189 offset:2048
	ds_read_b128 v[142:145], v189 offset:3072
	s_waitcnt vmcnt(6)
	s_barrier
	v_mfma_f32_16x16x32_bf16 v[54:57], v[194:197], v[158:161], v[54:57]
	v_mfma_f32_16x16x32_bf16 v[50:53], v[202:205], v[158:161], v[50:53]
	v_mfma_f32_16x16x32_bf16 v[38:41], v[194:197], v[166:169], v[38:41]
	v_mfma_f32_16x16x32_bf16 v[34:37], v[202:205], v[166:169], v[34:37]
	v_mfma_f32_16x16x32_bf16 v[22:25], v[194:197], v[176:179], v[22:25]
	v_mfma_f32_16x16x32_bf16 v[18:21], v[202:205], v[176:179], v[18:21]
	v_mfma_f32_16x16x32_bf16 v[6:9], v[194:197], v[184:187], v[6:9]
	v_mfma_f32_16x16x32_bf16 v[2:5], v[202:205], v[184:187], v[2:5]
	v_mfma_f32_16x16x32_bf16 v[54:57], v[198:201], v[162:165], v[54:57]
	v_mfma_f32_16x16x32_bf16 v[50:53], v[206:209], v[162:165], v[50:53]
	v_mfma_f32_16x16x32_bf16 v[38:41], v[198:201], v[172:175], v[38:41]
	v_mfma_f32_16x16x32_bf16 v[34:37], v[206:209], v[172:175], v[34:37]
	v_mfma_f32_16x16x32_bf16 v[22:25], v[198:201], v[180:183], v[22:25]
	v_mfma_f32_16x16x32_bf16 v[18:21], v[206:209], v[180:183], v[18:21]
	v_mfma_f32_16x16x32_bf16 v[6:9], v[198:201], v[190:193], v[6:9]
	v_mfma_f32_16x16x32_bf16 v[2:5], v[206:209], v[190:193], v[2:5]
	s_add_i32 s85, s85, 2
	s_add_u32 s88, s88, 0x100
	s_addc_u32 s89, s89, 0
	s_add_u32 s34, s34, 0x100
	s_addc_u32 s79, s79, 0
	s_add_u32 s87, s88, 0xfffc0080
	s_addc_u32 s90, s89, -1
	s_cmp_eq_u32 s85, 12
	s_cselect_b32 s93, s13, s90
	s_cselect_b32 s92, s22, s87
	s_cselect_b32 s91, s7, s79
	s_cselect_b32 s90, s23, s34
	s_cmp_gt_u32 s85, 13
	s_barrier
